# dual-GEMM epilogue: m_a and m_b gate loads hoisted in two rounds; lambda computed once per phase; static priority moved to waves 0-3
# speedup vs baseline: 1.0193x; 1.0029x over previous
; #define KP_ ([]() { unsigned long long q_ = (unsigned long long)__builtin_amdgcn_kernarg_segment_ptr(); asm volatile("" : "+s"(q_)); return (const __attribute__((address_space(4))) Params*)q_; }())
; __device__ __forceinline__ void attn_unit(LAS unsigned char* lds, bf16_t* Zg, const unsigned char* KVg, int S, int b, int h, int qb, const float* lq1, const float* lk1, const float* lq2, const float* lk2, const float* subln_g, const float* rel_bias, bool dostore = true) {
;     ...
;     const float lam = __builtin_amdgcn_exp2f(LOG2E * wave_sum(lq1[lane] * lk1[lane], lane)) - __builtin_amdgcn_exp2f(LOG2E * wave_sum(lq2[lane] * lk2[lane], lane)) + LAMBDA_INIT;
; __global__ void __launch_bounds__(NTHREADS, 2) fwd_megakernel(Params P, int ph_lo, int ph_hi, int use_sync) {
;     ...
;             const int nqb = S / 128, nunits = NB * 8 * nqb;
;             for (int u = vcu; u < nunits; u += G) { const int bh = u / nqb, qb = u % nqb; attn_unit(lds, Z, ws + WS_KV, S, bh >> 3, bh & 7, qb, KP_->lq1, KP_->lk1, KP_->lq2, KP_->lk2, KP_->subln_g, KP_->rel_bias); }
.LBB0_185:
	s_ff1_i32_b32 s4, s11
	s_lshr_b32 s4, 0x8000, s4
	s_lshr_b32 s43, s11, 4
	s_mul_i32 s43, s43, s4
	s_cmp_ge_i32 s82, s43
	v_readlane_b32 s72, v229, 15
	s_cbranch_scc1 .LBB0_291
	s_load_dwordx2 s[4:5], s[0:1], 0x20
	s_load_dwordx2 s[6:7], s[0:1], 0x28
	s_load_dwordx2 s[8:9], s[0:1], 0x30
	s_load_dwordx2 s[12:13], s[0:1], 0x38
	v_and_b32_e32 v66, 63, v204
	v_lshlrev_b32_e32 v66, 2, v66
	s_waitcnt lgkmcnt(0)
	global_load_dword v67, v66, s[4:5]
	global_load_dword v68, v66, s[6:7]
	global_load_dword v69, v66, s[8:9]
	global_load_dword v70, v66, s[12:13]
	v_xor_b32_e32 v84, 4, v66
	v_xor_b32_e32 v85, 8, v66
	v_xor_b32_e32 v86, 16, v66
	v_xor_b32_e32 v87, 32, v66
	v_xor_b32_e32 v88, 64, v66
	v_xor_b32_e32 v66, 0x80, v66
	s_waitcnt vmcnt(2)
	v_mul_f32_e32 v71, v67, v68
	ds_bpermute_b32 v71, v84, v71
	s_waitcnt vmcnt(0)
	v_mul_f32_e32 v72, v69, v70
	ds_bpermute_b32 v72, v84, v72
	s_waitcnt lgkmcnt(1)
	v_fmac_f32_e32 v71, v67, v68
	ds_bpermute_b32 v67, v85, v71
	s_waitcnt lgkmcnt(1)
	v_fmac_f32_e32 v72, v69, v70
	ds_bpermute_b32 v68, v85, v72
	s_waitcnt lgkmcnt(1)
	v_add_f32_e32 v67, v71, v67
	ds_bpermute_b32 v69, v86, v67
	s_waitcnt lgkmcnt(1)
	v_add_f32_e32 v68, v72, v68
	ds_bpermute_b32 v70, v86, v68
	s_waitcnt lgkmcnt(1)
	v_add_f32_e32 v67, v67, v69
	ds_bpermute_b32 v69, v87, v67
	s_waitcnt lgkmcnt(1)
	v_add_f32_e32 v68, v68, v70
	ds_bpermute_b32 v70, v87, v68
	s_waitcnt lgkmcnt(1)
	v_add_f32_e32 v67, v67, v69
	ds_bpermute_b32 v69, v88, v67
	s_waitcnt lgkmcnt(1)
	v_add_f32_e32 v68, v68, v70
	ds_bpermute_b32 v70, v88, v68
	s_waitcnt lgkmcnt(1)
	v_add_f32_e32 v67, v67, v69
	s_waitcnt lgkmcnt(0)
	v_add_f32_e32 v69, v68, v70
	ds_bpermute_b32 v68, v66, v67
	ds_bpermute_b32 v70, v66, v69
	s_waitcnt lgkmcnt(0)
	v_add_f32_e32 v69, v69, v70
	v_add_f32_e32 v67, v67, v68
	v_mul_f32_e32 v67, 0x3fb8aa3b, v67
	v_mul_f32_e32 v68, 0x3fb8aa3b, v69
	v_exp_f32_e32 v67, v67
	v_exp_f32_e32 v68, v68
	s_nop 0
	v_sub_f32_e32 v67, v67, v68
	v_add_f32_e32 v247, 0x3e4ccccd, v67
	s_lshr_b32 s66, s11, 7
	v_cvt_f32_ubyte0_e32 v0, s66
	v_writelane_b32 v229, s30, 19
	s_lshl_b32 s22, s11, 9
	s_add_i32 s4, s11, 0xffffff40
	v_rcp_iflag_f32_e32 v0, v0
	v_writelane_b32 v229, s4, 20
	s_add_i32 s5, s22, 0xffff0000
	v_writelane_b32 v229, s5, 21
	s_add_i32 s5, s11, 0xffffff7f
	v_writelane_b32 v229, s5, 22
	s_add_i32 s5, s11, 0xfffffee6
	v_writelane_b32 v229, s5, 23
	s_add_i32 s5, s22, 0xffff0400
	v_mul_f32_e32 v0, 0x4f7ffffe, v0
	v_writelane_b32 v229, s5, 24
	s_add_i32 s5, s22, 0xffffa000
	v_cvt_u32_f32_e32 v0, v0
	s_lshr_b32 s67, s11, 6
	v_writelane_b32 v229, s5, 25
	s_add_i32 s5, s11, 0xffffffbf
	s_add_i32 s4, s67, -1
	v_writelane_b32 v229, s5, 26
	s_add_i32 s5, s22, 0xffff8400
	s_lshl_b32 s46, s4, 15
	v_writelane_b32 v229, s5, 27
	s_lshl_b32 s4, s4, 6
	s_or_b32 s45, s4, 63
	v_writelane_b32 v229, s4, 28
	s_add_i32 s44, s4, 0xffffffa6
	s_sub_i32 s4, 0, s66
	v_readfirstlane_b32 s5, v0
	s_mul_i32 s4, s4, s5
	s_mul_hi_u32 s4, s5, s4
	s_add_i32 s24, s67, 0x1ffff
	s_add_i32 s58, s22, 0xffff8000
	s_add_i32 s41, s11, 0xffffff80
	s_or_b32 s48, s46, 0x2000
	s_sub_i32 s49, s11, 64
	s_add_i32 s34, s5, s4
	s_and_b32 s98, s11, 0x7f80
	s_mov_b32 s94, s82
	s_branch .LBB0_188

; #define STEP_CLOSE() do { asm volatile("s_waitcnt vmcnt(0)" ::: "memory"); asm volatile("s_waitcnt lgkmcnt(0)" ::: "memory"); __builtin_amdgcn_s_barrier(); asm volatile("" ::: "memory"); } while (0)
; #define SET_CINIT(k0v) do { const float ci_ = TILE_CB(k0v) - mhat; _Pragma("unroll") for (int r = 0; r < 16; ++r) cinit[r] = ci_; } while (0)
; __device__ __forceinline__ void attn_unit(LAS unsigned char* lds, bf16_t* Zg, const unsigned char* KVg, int S, int b, int h, int qb, const float* lq1, const float* lk1, const float* lq2, const float* lk2, const float* subln_g, const float* rel_bias, bool dostore = true) {
;     ...
;         float rm_ = fmaxf(pA0[0], pA1[0]);
; #pragma unroll
;         for (int r = 1; r < 16; ++r) rm_ = fmaxf(fmaxf(rm_, pA0[r]), pA1[r]);
;         { auto rr_ = __builtin_amdgcn_permlane32_swap(__float_as_uint(rm_), __float_as_uint(rm_), false, false); rm_ = fmaxf(__uint_as_float(rr_[0]), __uint_as_float(rr_[1])); }
;         mhat = rm_;
; #pragma unroll
;         for (int r = 0; r < 16; ++r) { pA0[r] = __builtin_amdgcn_exp2f(pA0[r] - rm_); pA1[r] = __builtin_amdgcn_exp2f(pA1[r] - rm_); }
;         SET_CINIT(64);
;         STEP_CLOSE();
;     ...
;     if (wid >= 4) __builtin_amdgcn_s_setprio(1);
.LBB0_208:
	s_nop 10
	v_max_f32_e32 v34, v2, v2
	v_max_f32_e32 v35, v18, v18
	v_max_f32_e32 v34, v35, v34
	v_max3_f32 v34, v34, v19, v3
	v_max3_f32 v34, v34, v20, v4
	v_max3_f32 v34, v34, v21, v5
	v_max3_f32 v34, v34, v22, v6
	v_max3_f32 v34, v34, v23, v7
	v_max3_f32 v34, v34, v24, v8
	v_max3_f32 v34, v34, v25, v9
	v_max3_f32 v34, v34, v26, v10
	v_max3_f32 v34, v34, v27, v11
	v_max3_f32 v34, v34, v28, v12
	v_max3_f32 v34, v34, v29, v13
	v_max3_f32 v34, v34, v30, v14
	v_max3_f32 v34, v34, v31, v15
	v_max3_f32 v34, v34, v32, v16
	s_cmpk_gt_i32 s78, 0xd9
	s_waitcnt vmcnt(0)
	v_max3_f32 v34, v34, v33, v17
	s_cselect_b64 vcc, -1, 0
	s_or_b32 s79, s78, 31
	s_waitcnt lgkmcnt(0)
	s_barrier
	v_mov_b32_e32 v35, v34
	s_cmpk_lt_i32 s79, 0xffe6
	s_nop 0
	v_permlane32_swap_b32_e32 v34, v35
	s_cselect_b64 s[4:5], -1, 0
	s_cmp_ge_i32 s29, 4
	s_cbranch_scc1 .LBB0_210
	s_setprio 1

; __device__ __forceinline__ void attn_unit(LAS unsigned char* lds, bf16_t* Zg, const unsigned char* KVg, int S, int b, int h, int qb, const float* lq1, const float* lk1, const float* lq2, const float* lk2, const float* subln_g, const float* rel_bias, bool dostore = true) {
;     ...
;     STEP(false, false, false, pA0, pA1, pB0, pB1, NT, 0);
;     __builtin_amdgcn_s_setprio(0);
;     asm volatile("s_waitcnt vmcnt(0)" ::: "memory");
;     __syncthreads();
;     ...
;     { auto rr_ = __builtin_amdgcn_permlane32_swap(__float_as_uint(lsum), __float_as_uint(lsum), false, false); lsum = __uint_as_float(rr_[0]) + __uint_as_float(rr_[1]); }
;     const float lam = __builtin_amdgcn_exp2f(LOG2E * wave_sum(lq1[lane] * lk1[lane], lane)) - __builtin_amdgcn_exp2f(LOG2E * wave_sum(lq2[lane] * lk2[lane], lane)) + LAMBDA_INIT;
;     if (hi == 0) wsf[r32] = (mp == 1 ? lam : 1.0f) / lsum;
.LBB0_283:
	v_add_f32_e32 v0, v82, v83
	v_add_f32_e32 v99, v84, v85
	v_add_f32_e32 v0, v0, v99
	v_add_f32_e32 v0, 0, v0
	v_cvt_pk_bf16_f32 v175, v84, v85
	v_cvt_pk_bf16_f32 v174, v82, v83
	v_add_f32_e32 v82, v86, v87
	v_add_f32_e32 v83, v88, v89
	v_add_f32_e32 v82, v82, v83
	v_add_f32_e32 v0, v0, v82
	v_cvt_pk_bf16_f32 v177, v88, v89
	v_cvt_pk_bf16_f32 v176, v86, v87
	v_add_f32_e32 v82, v90, v91
	v_add_f32_e32 v83, v92, v93
	v_add_f32_e32 v82, v82, v83
	v_add_f32_e32 v0, v82, v0
	v_cvt_pk_bf16_f32 v170, v90, v91
	v_cvt_pk_bf16_f32 v171, v92, v93
	v_add_f32_e32 v82, v94, v95
	v_add_f32_e32 v83, v96, v97
	v_add_f32_e32 v82, v82, v83
	v_add_f32_e32 v0, v82, v0
	v_cvt_pk_bf16_f32 v172, v94, v95
	v_cvt_pk_bf16_f32 v173, v96, v97
	v_add_f32_e32 v82, v66, v67
	v_add_f32_e32 v83, v68, v69
	v_add_f32_e32 v82, v82, v83
	v_add_f32_e32 v0, v82, v0
	v_cvt_pk_bf16_f32 v166, v66, v67
	v_cvt_pk_bf16_f32 v167, v68, v69
	v_add_f32_e32 v66, v70, v71
	v_add_f32_e32 v67, v72, v73
	v_add_f32_e32 v66, v66, v67
	v_add_f32_e32 v0, v66, v0
	v_cvt_pk_bf16_f32 v168, v70, v71
	v_cvt_pk_bf16_f32 v169, v72, v73
	v_add_f32_e32 v66, v74, v75
	v_add_f32_e32 v67, v76, v77
	v_add_f32_e32 v66, v66, v67
	v_add_f32_e32 v0, v66, v0
	v_cvt_pk_bf16_f32 v162, v74, v75
	v_cvt_pk_bf16_f32 v163, v76, v77
	v_add_f32_e32 v66, v78, v79
	v_add_f32_e32 v67, v80, v81
	v_add_f32_e32 v66, v66, v67
	v_add_f32_e32 v0, v66, v0
	v_cvt_pk_bf16_f32 v164, v78, v79
	v_cvt_pk_bf16_f32 v165, v80, v81
	ds_read_b64_tr_b16 v[66:67], v214 offset:0
	ds_read_b64_tr_b16 v[68:69], v214 offset:512
	ds_read_b64_tr_b16 v[70:71], v214 offset:4096
	ds_read_b64_tr_b16 v[72:73], v214 offset:4608
	ds_read_b64_tr_b16 v[74:75], v214 offset:8192
	ds_read_b64_tr_b16 v[76:77], v214 offset:8704
	ds_read_b64_tr_b16 v[78:79], v214 offset:12288
	ds_read_b64_tr_b16 v[80:81], v214 offset:12800
	s_waitcnt lgkmcnt(6)
	s_nop 0
	s_nop 0
	v_mfma_f32_32x32x16_bf16 v[50:65], v[174:177], v[66:69], v[50:65]
	ds_read_b64_tr_b16 v[66:67], v214 offset:1024
	ds_read_b64_tr_b16 v[68:69], v214 offset:1536
	s_waitcnt lgkmcnt(6)
	s_nop 0
	v_mfma_f32_32x32x16_bf16 v[34:49], v[174:177], v[70:73], v[34:49]
	ds_read_b64_tr_b16 v[70:71], v214 offset:5120
	ds_read_b64_tr_b16 v[72:73], v214 offset:5632
	s_waitcnt lgkmcnt(6)
	s_nop 0
	v_mfma_f32_32x32x16_bf16 v[18:33], v[174:177], v[74:77], v[18:33]
	ds_read_b64_tr_b16 v[74:75], v214 offset:9216
	ds_read_b64_tr_b16 v[76:77], v214 offset:9728
	s_waitcnt lgkmcnt(6)
	s_nop 0
	v_mfma_f32_32x32x16_bf16 v[2:17], v[174:177], v[78:81], v[2:17]
	ds_read_b64_tr_b16 v[78:79], v214 offset:13312
	ds_read_b64_tr_b16 v[80:81], v214 offset:13824
	s_waitcnt lgkmcnt(6)
	s_nop 0
	v_mfma_f32_32x32x16_bf16 v[50:65], v[170:173], v[66:69], v[50:65]
	ds_read_b64_tr_b16 v[66:67], v214 offset:2048
	ds_read_b64_tr_b16 v[68:69], v214 offset:2560
	s_waitcnt lgkmcnt(6)
	s_nop 0
	v_mfma_f32_32x32x16_bf16 v[34:49], v[170:173], v[70:73], v[34:49]
	ds_read_b64_tr_b16 v[70:71], v214 offset:6144
	ds_read_b64_tr_b16 v[72:73], v214 offset:6656
	s_waitcnt lgkmcnt(6)
	s_nop 0
	v_mfma_f32_32x32x16_bf16 v[18:33], v[170:173], v[74:77], v[18:33]
	ds_read_b64_tr_b16 v[74:75], v214 offset:10240
	ds_read_b64_tr_b16 v[76:77], v214 offset:10752
	s_waitcnt lgkmcnt(6)
	s_nop 0
	v_mfma_f32_32x32x16_bf16 v[2:17], v[170:173], v[78:81], v[2:17]
	ds_read_b64_tr_b16 v[78:79], v214 offset:14336
	ds_read_b64_tr_b16 v[80:81], v214 offset:14848
	s_waitcnt lgkmcnt(6)
	s_nop 0
	v_mfma_f32_32x32x16_bf16 v[50:65], v[166:169], v[66:69], v[50:65]
	ds_read_b64_tr_b16 v[66:67], v214 offset:3072
	ds_read_b64_tr_b16 v[68:69], v214 offset:3584
	s_waitcnt lgkmcnt(6)
	s_nop 0
	v_mfma_f32_32x32x16_bf16 v[34:49], v[166:169], v[70:73], v[34:49]
	ds_read_b64_tr_b16 v[70:71], v214 offset:7168
	ds_read_b64_tr_b16 v[72:73], v214 offset:7680
	s_waitcnt lgkmcnt(6)
	s_nop 0
	v_mfma_f32_32x32x16_bf16 v[18:33], v[166:169], v[74:77], v[18:33]
	ds_read_b64_tr_b16 v[74:75], v214 offset:11264
	ds_read_b64_tr_b16 v[76:77], v214 offset:11776
	s_waitcnt lgkmcnt(6)
	s_nop 0
	v_mfma_f32_32x32x16_bf16 v[2:17], v[166:169], v[78:81], v[2:17]
	ds_read_b64_tr_b16 v[78:79], v214 offset:15360
	ds_read_b64_tr_b16 v[80:81], v214 offset:15872
	s_waitcnt lgkmcnt(6)
	s_nop 0
	v_mfma_f32_32x32x16_bf16 v[50:65], v[162:165], v[66:69], v[50:65]
	s_waitcnt lgkmcnt(4)
	s_nop 0
	v_mfma_f32_32x32x16_bf16 v[34:49], v[162:165], v[70:73], v[34:49]
	s_waitcnt lgkmcnt(2)
	s_nop 0
	v_mfma_f32_32x32x16_bf16 v[18:33], v[162:165], v[74:77], v[18:33]
	s_waitcnt lgkmcnt(0)
	s_nop 0
	v_mfma_f32_32x32x16_bf16 v[2:17], v[162:165], v[78:81], v[2:17]
	v_add_f32_e32 v0, v98, v0
	s_setprio 0
	v_lshlrev_b32_e32 v66, 2, v209
	s_waitcnt vmcnt(0)
	s_waitcnt vmcnt(0)
	s_barrier
	v_xor_b32_e32 v84, 4, v66
	v_xor_b32_e32 v85, 8, v66
	v_xor_b32_e32 v86, 16, v66
	v_xor_b32_e32 v87, 32, v66
	v_xor_b32_e32 v88, 64, v66
	v_mov_b32_e32 v66, v0
	s_nop 1
	v_permlane32_swap_b32_e32 v0, v66
	s_and_saveexec_b64 s[6:7], s[4:5]
	s_cbranch_execz .LBB0_285
	s_waitcnt lgkmcnt(0)
	s_cmp_eq_u32 s89, 1
	s_cselect_b64 vcc, -1, 0
	v_add_f32_e32 v0, v0, v66
	v_cndmask_b32_e32 v66, 1.0, v247, vcc
	v_div_scale_f32 v67, s[4:5], v0, v0, v66
	v_rcp_f32_e32 v68, v67
	s_nop 0
	v_fma_f32 v69, -v67, v68, 1.0
	v_fmac_f32_e32 v68, v69, v68
	v_div_scale_f32 v69, vcc, v66, v0, v66
	v_mul_f32_e32 v70, v69, v68
	v_fma_f32 v71, -v67, v70, v69
	v_fmac_f32_e32 v70, v71, v68
	v_fma_f32 v67, -v67, v70, v69
	v_div_fmas_f32 v67, v67, v68, v70
	v_div_fixup_f32 v0, v67, v0, v66
	ds_write_b32 v213, v0

; __device__ __forceinline__ float bf_lo(unsigned w) { return __uint_as_float(w << 16); }
; __device__ __forceinline__ float bf_hi(unsigned w) { return __uint_as_float(w & 0xffff0000u); }
;     __device__ __forceinline__ void operator()(f32x4 (&acc)[2][2][4][2], const Unit& u, int wr, int wc, int fr, int fq) const {
;     ...
;             for (int m = 0; m < 4; ++m) { const int r = row0 + ai * HALF + m * 16;
; #pragma unroll
;                 for (int bj = 0; bj < 2; ++bj) { const int c = col0 + bj * HALF;
;                     const u32x4 gb = *(const u32x4*)(Gb + (size_t)r * ldg + c);
;                     float eb[8];
; #pragma unroll
;                     for (int e = 0; e < 4; ++e) { eb[2 * e] = __builtin_amdgcn_exp2f(-1.4426950408889634f * bf_lo(gb[e])); eb[2 * e + 1] = __builtin_amdgcn_exp2f(-1.4426950408889634f * bf_hi(gb[e])); }
;                     if (u.half == 0) { const u32x4 ga = *(const u32x4*)(Ga + (size_t)r * ldg + c);
; #pragma unroll
;                         for (int e = 0; e < 4; ++e) { const float ea0 = __builtin_amdgcn_exp2f(-1.4426950408889634f * bf_lo(ga[e])), ea1 = __builtin_amdgcn_exp2f(-1.4426950408889634f * bf_hi(ga[e]));
;                             acc[ai][bj][m][e >> 1][(2 * e) & 3] *= (1.0f + eb[2 * e]) * __builtin_amdgcn_rcpf(1.0f + ea0);
;                             acc[ai][bj][m][e >> 1][(2 * e + 1) & 3] *= (1.0f + eb[2 * e + 1]) * __builtin_amdgcn_rcpf(1.0f + ea1); } }
.LBB0_322:
	v_lshl_add_u32 v132, s31, 8, v152
	v_lshl_or_b32 v2, s30, 8, v153
	v_mad_i64_i32 v[138:139], s[8:9], v132, s90, 0
	v_lshl_add_u64 v[134:135], v[138:139], 1, s[72:73]
	v_ashrrev_i32_e32 v3, 31, v2
	v_lshl_add_u64 v[136:137], v[2:3], 1, v[134:135]
	global_load_dwordx4 v[140:143], v[136:137], off
	global_load_dwordx4 v[162:165], v[136:137], off offset:256
	v_add_co_u32_e32 v226, vcc, 0x48000, v136
	s_nop 1
	v_addc_co_u32_e32 v227, vcc, 0, v137, vcc
	global_load_dwordx4 v[166:169], v[226:227], off
	global_load_dwordx4 v[170:173], v[226:227], off offset:256
	v_add_co_u32_e32 v226, vcc, 0x90000, v136
	s_nop 1
	v_addc_co_u32_e32 v227, vcc, 0, v137, vcc
	global_load_dwordx4 v[174:177], v[226:227], off
	global_load_dwordx4 v[178:181], v[226:227], off offset:256
	v_add_co_u32_e32 v226, vcc, 0xd8000, v136
	s_nop 1
	v_addc_co_u32_e32 v227, vcc, 0, v137, vcc
	global_load_dwordx4 v[182:185], v[226:227], off
	global_load_dwordx4 v[186:189], v[226:227], off offset:256
	s_cmp_lg_u32 s10, 0
	s_cbranch_scc1 .Lepid_skip_A
	global_load_dwordx4 v[190:193], v[136:137], off offset:-2048
	global_load_dwordx4 v[210:213], v[136:137], off offset:-1792
	v_add_co_u32_e32 v226, vcc, 0x48000, v136
	s_nop 1
	v_addc_co_u32_e32 v227, vcc, 0, v137, vcc
	global_load_dwordx4 v[214:217], v[226:227], off offset:-2048
	global_load_dwordx4 v[218:221], v[226:227], off offset:-1792
	v_add_co_u32_e32 v226, vcc, 0x90000, v136
	s_nop 1
	v_addc_co_u32_e32 v227, vcc, 0, v137, vcc
	global_load_dwordx4 v[222:225], v[226:227], off offset:-2048
	global_load_dwordx4 v[230:233], v[226:227], off offset:-1792
	v_add_co_u32_e32 v226, vcc, 0xd8000, v136
	s_nop 1
	v_addc_co_u32_e32 v227, vcc, 0, v137, vcc
	global_load_dwordx4 v[234:237], v[226:227], off offset:-2048
	.Lepid_skip_A:
	v_ashrrev_i32_e32 v133, 31, v132
	s_cmp_lg_u32 s10, 0
	s_cselect_b64 s[26:27], -1, 0
	s_cmp_eq_u32 s10, 0
	s_waitcnt vmcnt(7)
	v_lshlrev_b32_e32 v0, 16, v140
	v_and_b32_e32 v134, 0xffff0000, v140
	v_lshlrev_b32_e32 v135, 16, v141
	v_and_b32_e32 v140, 0xffff0000, v141
	v_lshlrev_b32_e32 v141, 16, v142
	v_and_b32_e32 v142, 0xffff0000, v142
	v_lshlrev_b32_e32 v144, 16, v143
	v_and_b32_e32 v143, 0xffff0000, v143
	v_mul_f32_e32 v0, 0xbfb8aa3b, v0
	v_mul_f32_e32 v134, 0xbfb8aa3b, v134
	v_mul_f32_e32 v135, 0xbfb8aa3b, v135
	v_mul_f32_e32 v140, 0xbfb8aa3b, v140
	v_mul_f32_e32 v141, 0xbfb8aa3b, v141
	v_mul_f32_e32 v142, 0xbfb8aa3b, v142
	v_mul_f32_e32 v156, 0xbfb8aa3b, v144
	v_mul_f32_e32 v143, 0xbfb8aa3b, v143
	v_exp_f32_e32 v144, v0
	v_exp_f32_e32 v145, v134
	v_exp_f32_e32 v146, v135
	v_exp_f32_e32 v147, v140
	v_exp_f32_e32 v140, v141
	v_exp_f32_e32 v141, v142
	v_exp_f32_e32 v142, v156
	v_exp_f32_e32 v143, v143
	v_lshlrev_b64 v[134:135], 11, v[132:133]
	v_lshl_add_u64 v[134:135], s[74:75], 0, v[134:135]
	s_cbranch_scc1 .LBB0_373
	v_add_f32_e32 v0, 1.0, v144
	v_rcp_f32_e32 v156, v0
	v_add_f32_e32 v0, 1.0, v145
	v_rcp_f32_e32 v157, v0
	v_add_f32_e32 v0, 1.0, v146
	v_rcp_f32_e32 v158, v0
	v_add_f32_e32 v0, 1.0, v147
	v_rcp_f32_e32 v159, v0
	v_pk_mul_f32 v[156:157], v[128:129], v[156:157]
	v_add_f32_e32 v0, 1.0, v140
	v_cvt_pk_bf16_f32 v156, v156, v157
	v_pk_mul_f32 v[158:159], v[130:131], v[158:159]
	s_nop 0
	v_cvt_pk_bf16_f32 v157, v158, v159
	v_rcp_f32_e32 v158, v0
	v_add_f32_e32 v0, 1.0, v141
	v_rcp_f32_e32 v159, v0
	v_add_f32_e32 v0, 1.0, v142
	v_rcp_f32_e32 v160, v0
	v_add_f32_e32 v0, 1.0, v143
	v_rcp_f32_e32 v161, v0
	v_pk_mul_f32 v[158:159], v[124:125], v[158:159]
	v_pk_mul_f32 v[160:161], v[126:127], v[160:161]
	v_cvt_pk_bf16_f32 v158, v158, v159
	v_cvt_pk_bf16_f32 v159, v160, v161
	v_lshl_add_u64 v[160:161], v[2:3], 1, v[134:135]
	global_store_dwordx4 v[160:161], v[156:159], off
	v_lshl_add_u64 v[138:139], v[138:139], 1, s[70:71]
	s_cbranch_execnz .LBB0_325
.LBB0_324:
	v_lshl_add_u64 v[156:157], v[2:3], 1, v[138:139]
	v_pk_add_f32 v[144:145], v[144:145], 1.0 op_sel_hi:[1,0]
	v_pk_add_f32 v[146:147], v[146:147], 1.0 op_sel_hi:[1,0]
	v_pk_add_f32 v[142:143], v[142:143], 1.0 op_sel_hi:[1,0]
	v_pk_add_f32 v[140:141], v[140:141], 1.0 op_sel_hi:[1,0]
	s_waitcnt vmcnt(6)
	v_mov_b64_e32 v[156:157], v[190:191]
	v_mov_b64_e32 v[158:159], v[192:193]
	v_lshlrev_b32_e32 v0, 16, v156
	v_mul_f32_e32 v0, 0xbfb8aa3b, v0
	v_and_b32_e32 v133, 0xffff0000, v156
	v_exp_f32_e32 v0, v0
	v_mul_f32_e32 v133, 0xbfb8aa3b, v133
	v_exp_f32_e32 v133, v133
	v_add_f32_e32 v0, 1.0, v0
	v_rcp_f32_e32 v160, v0
	v_add_f32_e32 v0, 1.0, v133
	v_rcp_f32_e32 v161, v0
	v_lshlrev_b32_e32 v0, 16, v157
	v_mul_f32_e32 v0, 0xbfb8aa3b, v0
	v_and_b32_e32 v133, 0xffff0000, v157
	v_exp_f32_e32 v0, v0
	v_mul_f32_e32 v133, 0xbfb8aa3b, v133
	v_exp_f32_e32 v133, v133
	v_pk_mul_f32 v[144:145], v[144:145], v[160:161]
	v_add_f32_e32 v0, 1.0, v0
	v_rcp_f32_e32 v156, v0
	v_add_f32_e32 v0, 1.0, v133
	v_rcp_f32_e32 v157, v0
	v_lshlrev_b32_e32 v0, 16, v158
	v_mul_f32_e32 v0, 0xbfb8aa3b, v0
	v_and_b32_e32 v133, 0xffff0000, v158
	v_exp_f32_e32 v0, v0
	v_mul_f32_e32 v133, 0xbfb8aa3b, v133
	v_exp_f32_e32 v133, v133
	v_pk_mul_f32 v[128:129], v[128:129], v[144:145]
	v_add_f32_e32 v0, 1.0, v0
	v_rcp_f32_e32 v144, v0
	v_add_f32_e32 v0, 1.0, v133
	v_rcp_f32_e32 v145, v0
	v_lshlrev_b32_e32 v0, 16, v159
	v_mul_f32_e32 v0, 0xbfb8aa3b, v0
	v_and_b32_e32 v133, 0xffff0000, v159
	v_exp_f32_e32 v0, v0
	v_mul_f32_e32 v133, 0xbfb8aa3b, v133
	v_exp_f32_e32 v133, v133
	v_pk_mul_f32 v[146:147], v[146:147], v[156:157]
	v_add_f32_e32 v0, 1.0, v0
	v_pk_mul_f32 v[130:131], v[130:131], v[146:147]
	v_rcp_f32_e32 v146, v0
	v_add_f32_e32 v0, 1.0, v133
	v_rcp_f32_e32 v147, v0
	v_pk_mul_f32 v[140:141], v[140:141], v[144:145]
	v_pk_mul_f32 v[142:143], v[142:143], v[146:147]
	s_nop 0
	v_pk_mul_f32 v[126:127], v[126:127], v[142:143]
	v_pk_mul_f32 v[124:125], v[124:125], v[140:141]
; __device__ __forceinline__ unsigned cvt_pk_bf16(float lo, float hi) { f32x2 v = {lo, hi}; bf16x2_t b = __builtin_convertvector(v, bf16x2_t); return __builtin_bit_cast(unsigned, b); }
; __device__ __forceinline__ float bf_lo(unsigned w) { return __uint_as_float(w << 16); }
; __device__ __forceinline__ float bf_hi(unsigned w) { return __uint_as_float(w & 0xffff0000u); }
;     __device__ __forceinline__ void operator()(f32x4 (&acc)[2][2][4][2], const Unit& u, int wr, int wc, int fr, int fq) const {
;     ...
;                 for (int bj = 0; bj < 2; ++bj) { const int c = col0 + bj * HALF;
;                     const u32x4 gb = *(const u32x4*)(Gb + (size_t)r * ldg + c);
;                     float eb[8];
; #pragma unroll
;                     for (int e = 0; e < 4; ++e) { eb[2 * e] = __builtin_amdgcn_exp2f(-1.4426950408889634f * bf_lo(gb[e])); eb[2 * e + 1] = __builtin_amdgcn_exp2f(-1.4426950408889634f * bf_hi(gb[e])); }
;                     if (u.half == 0) { const u32x4 ga = *(const u32x4*)(Ga + (size_t)r * ldg + c);
; #pragma unroll
;                         for (int e = 0; e < 4; ++e) { const float ea0 = __builtin_amdgcn_exp2f(-1.4426950408889634f * bf_lo(ga[e])), ea1 = __builtin_amdgcn_exp2f(-1.4426950408889634f * bf_hi(ga[e]));
;                             acc[ai][bj][m][e >> 1][(2 * e) & 3] *= (1.0f + eb[2 * e]) * __builtin_amdgcn_rcpf(1.0f + ea0);
;                             acc[ai][bj][m][e >> 1][(2 * e + 1) & 3] *= (1.0f + eb[2 * e + 1]) * __builtin_amdgcn_rcpf(1.0f + ea1); } }
;                     else { u32x4 w;
; #pragma unroll
;                         for (int e = 0; e < 4; ++e) { const float a0 = acc[ai][bj][m][e >> 1][(2 * e) & 3] * __builtin_amdgcn_rcpf(1.0f + eb[2 * e]), a1 = acc[ai][bj][m][e >> 1][(2 * e + 1) & 3] * __builtin_amdgcn_rcpf(1.0f + eb[2 * e + 1]);
;                             w[e] = cvt_pk_bf16(a0, a1); }
;                         *(u32x4*)(O + (size_t)r * ldo + c) = w; } } }
.LBB0_325:
	s_andn2_b64 vcc, exec, s[26:27]
	s_waitcnt vmcnt(7)
	v_mov_b64_e32 v[140:141], v[162:163]
	v_mov_b64_e32 v[142:143], v[164:165]
	v_lshlrev_b32_e32 v0, 16, v140
	v_and_b32_e32 v133, 0xffff0000, v140
	v_lshlrev_b32_e32 v136, 16, v141
	v_and_b32_e32 v137, 0xffff0000, v141
	v_lshlrev_b32_e32 v140, 16, v142
	v_and_b32_e32 v141, 0xffff0000, v142
	v_lshlrev_b32_e32 v142, 16, v143
	v_and_b32_e32 v143, 0xffff0000, v143
	v_mul_f32_e32 v0, 0xbfb8aa3b, v0
	v_mul_f32_e32 v133, 0xbfb8aa3b, v133
	v_mul_f32_e32 v136, 0xbfb8aa3b, v136
	v_mul_f32_e32 v137, 0xbfb8aa3b, v137
	v_mul_f32_e32 v140, 0xbfb8aa3b, v140
	v_mul_f32_e32 v141, 0xbfb8aa3b, v141
	v_mul_f32_e32 v146, 0xbfb8aa3b, v142
	v_mul_f32_e32 v147, 0xbfb8aa3b, v143
	v_exp_f32_e32 v142, v0
	v_exp_f32_e32 v143, v133
	v_exp_f32_e32 v144, v136
	v_exp_f32_e32 v145, v137
	v_exp_f32_e32 v136, v140
	v_exp_f32_e32 v137, v141
	v_exp_f32_e32 v140, v146
	v_exp_f32_e32 v141, v147
	v_cndmask_b32_e64 v0, 0, 1, s[26:27]
	v_cmp_ne_u32_e64 s[8:9], 1, v0
	s_cbranch_vccnz .LBB0_374
	v_add_f32_e32 v0, 1.0, v142
	v_rcp_f32_e32 v146, v0
	v_add_f32_e32 v0, 1.0, v143
	v_rcp_f32_e32 v147, v0
	v_add_f32_e32 v0, 1.0, v144
	v_lshl_add_u64 v[134:135], v[2:3], 1, v[134:135]
	v_pk_mul_f32 v[146:147], v[96:97], v[146:147]
	s_nop 0
	v_cvt_pk_bf16_f32 v156, v146, v147
	v_rcp_f32_e32 v146, v0
	v_add_f32_e32 v0, 1.0, v145
	v_rcp_f32_e32 v147, v0
	v_add_f32_e32 v0, 1.0, v136
	v_pk_mul_f32 v[146:147], v[98:99], v[146:147]
	s_nop 0
	v_cvt_pk_bf16_f32 v157, v146, v147
	v_rcp_f32_e32 v146, v0
	v_add_f32_e32 v0, 1.0, v137
	v_rcp_f32_e32 v147, v0
	v_add_f32_e32 v0, 1.0, v140
	v_pk_mul_f32 v[146:147], v[92:93], v[146:147]
	s_nop 0
	v_cvt_pk_bf16_f32 v158, v146, v147
	v_rcp_f32_e32 v146, v0
	v_add_f32_e32 v0, 1.0, v141
	v_rcp_f32_e32 v147, v0
	s_nop 0
	v_pk_mul_f32 v[146:147], v[94:95], v[146:147]
	s_nop 0
	v_cvt_pk_bf16_f32 v159, v146, v147
	global_store_dwordx4 v[134:135], v[156:159], off offset:256
	s_cbranch_execnz .LBB0_328
.LBB0_327:
	v_lshl_add_u64 v[134:135], v[2:3], 1, v[138:139]
	v_pk_add_f32 v[142:143], v[142:143], 1.0 op_sel_hi:[1,0]
	v_pk_add_f32 v[144:145], v[144:145], 1.0 op_sel_hi:[1,0]
	v_pk_add_f32 v[140:141], v[140:141], 1.0 op_sel_hi:[1,0]
	v_pk_add_f32 v[136:137], v[136:137], 1.0 op_sel_hi:[1,0]
	s_waitcnt vmcnt(5)
	v_mov_b64_e32 v[156:157], v[210:211]
	v_mov_b64_e32 v[158:159], v[212:213]
	v_lshlrev_b32_e32 v0, 16, v156
	v_mul_f32_e32 v0, 0xbfb8aa3b, v0
	v_and_b32_e32 v133, 0xffff0000, v156
	v_exp_f32_e32 v0, v0
	v_mul_f32_e32 v133, 0xbfb8aa3b, v133
	v_exp_f32_e32 v133, v133
	v_add_f32_e32 v0, 1.0, v0
	v_rcp_f32_e32 v134, v0
	v_add_f32_e32 v0, 1.0, v133
	v_rcp_f32_e32 v135, v0
	v_lshlrev_b32_e32 v0, 16, v157
	v_mul_f32_e32 v0, 0xbfb8aa3b, v0
	v_and_b32_e32 v133, 0xffff0000, v157
	v_exp_f32_e32 v0, v0
	v_mul_f32_e32 v133, 0xbfb8aa3b, v133
	v_exp_f32_e32 v133, v133
	v_pk_mul_f32 v[134:135], v[142:143], v[134:135]
	v_add_f32_e32 v0, 1.0, v0
	v_rcp_f32_e32 v138, v0
	v_add_f32_e32 v0, 1.0, v133
	v_rcp_f32_e32 v139, v0
	v_lshlrev_b32_e32 v0, 16, v158
	v_mul_f32_e32 v0, 0xbfb8aa3b, v0
	v_and_b32_e32 v133, 0xffff0000, v158
	v_exp_f32_e32 v0, v0
	v_mul_f32_e32 v133, 0xbfb8aa3b, v133
	v_exp_f32_e32 v133, v133
	v_pk_mul_f32 v[96:97], v[96:97], v[134:135]
	v_add_f32_e32 v0, 1.0, v0
	v_rcp_f32_e32 v134, v0
	v_add_f32_e32 v0, 1.0, v133
	v_rcp_f32_e32 v135, v0
	v_lshlrev_b32_e32 v0, 16, v159
	v_mul_f32_e32 v0, 0xbfb8aa3b, v0
	v_and_b32_e32 v133, 0xffff0000, v159
	v_exp_f32_e32 v0, v0
	v_mul_f32_e32 v133, 0xbfb8aa3b, v133
	v_exp_f32_e32 v133, v133
	v_pk_mul_f32 v[138:139], v[144:145], v[138:139]
	v_add_f32_e32 v0, 1.0, v0
	v_pk_mul_f32 v[98:99], v[98:99], v[138:139]
	v_rcp_f32_e32 v138, v0
	v_add_f32_e32 v0, 1.0, v133
	v_rcp_f32_e32 v139, v0
	v_pk_mul_f32 v[134:135], v[136:137], v[134:135]
	v_pk_mul_f32 v[136:137], v[140:141], v[138:139]
	s_nop 0
	v_pk_mul_f32 v[94:95], v[94:95], v[136:137]
	v_pk_mul_f32 v[92:93], v[92:93], v[134:135]
.LBB0_328:
	v_or_b32_e32 v134, 16, v132
	v_mad_i64_i32 v[138:139], s[26:27], v134, s90, 0
	v_lshl_add_u64 v[136:137], v[138:139], 1, s[72:73]
	v_lshl_add_u64 v[136:137], v[2:3], 1, v[136:137]
	v_ashrrev_i32_e32 v135, 31, v134
	v_lshlrev_b64 v[134:135], 11, v[134:135]
	s_and_b64 vcc, exec, s[8:9]
	v_lshl_add_u64 v[134:135], s[74:75], 0, v[134:135]
	s_waitcnt vmcnt(7)
	v_mov_b64_e32 v[140:141], v[166:167]
	v_mov_b64_e32 v[142:143], v[168:169]
	v_lshlrev_b32_e32 v0, 16, v140
	v_and_b32_e32 v133, 0xffff0000, v140
	v_lshlrev_b32_e32 v140, 16, v141
	v_and_b32_e32 v141, 0xffff0000, v141
	v_lshlrev_b32_e32 v144, 16, v142
	v_and_b32_e32 v142, 0xffff0000, v142
	v_lshlrev_b32_e32 v145, 16, v143
	v_and_b32_e32 v143, 0xffff0000, v143
	v_mul_f32_e32 v0, 0xbfb8aa3b, v0
	v_mul_f32_e32 v133, 0xbfb8aa3b, v133
	v_mul_f32_e32 v140, 0xbfb8aa3b, v140
	v_mul_f32_e32 v141, 0xbfb8aa3b, v141
	v_mul_f32_e32 v156, 0xbfb8aa3b, v144
	v_mul_f32_e32 v142, 0xbfb8aa3b, v142
	v_mul_f32_e32 v157, 0xbfb8aa3b, v145
	v_mul_f32_e32 v143, 0xbfb8aa3b, v143
	v_exp_f32_e32 v144, v0
	v_exp_f32_e32 v145, v133
	v_exp_f32_e32 v146, v140
	v_exp_f32_e32 v147, v141
	v_exp_f32_e32 v140, v156
	v_exp_f32_e32 v141, v142
	v_exp_f32_e32 v142, v157
	v_exp_f32_e32 v143, v143
	s_cbranch_vccnz .LBB0_375
	v_add_f32_e32 v0, 1.0, v144
	v_rcp_f32_e32 v156, v0
	v_add_f32_e32 v0, 1.0, v145
	v_rcp_f32_e32 v157, v0
	v_add_f32_e32 v0, 1.0, v146
	v_rcp_f32_e32 v158, v0
	v_add_f32_e32 v0, 1.0, v147
	v_rcp_f32_e32 v159, v0
	v_pk_mul_f32 v[156:157], v[120:121], v[156:157]
	v_add_f32_e32 v0, 1.0, v140
	v_cvt_pk_bf16_f32 v156, v156, v157
	v_pk_mul_f32 v[158:159], v[122:123], v[158:159]
	s_nop 0
	v_cvt_pk_bf16_f32 v157, v158, v159
	v_rcp_f32_e32 v158, v0
	v_add_f32_e32 v0, 1.0, v141
	v_rcp_f32_e32 v159, v0
	v_add_f32_e32 v0, 1.0, v142
	v_rcp_f32_e32 v160, v0
	v_add_f32_e32 v0, 1.0, v143
	v_rcp_f32_e32 v161, v0
	v_pk_mul_f32 v[158:159], v[116:117], v[158:159]
	v_pk_mul_f32 v[160:161], v[118:119], v[160:161]
	v_cvt_pk_bf16_f32 v158, v158, v159
	v_cvt_pk_bf16_f32 v159, v160, v161
	v_lshl_add_u64 v[160:161], v[2:3], 1, v[134:135]
	global_store_dwordx4 v[160:161], v[156:159], off
	v_lshl_add_u64 v[138:139], v[138:139], 1, s[70:71]
	s_cbranch_execnz .LBB0_331
; __device__ __forceinline__ unsigned cvt_pk_bf16(float lo, float hi) { f32x2 v = {lo, hi}; bf16x2_t b = __builtin_convertvector(v, bf16x2_t); return __builtin_bit_cast(unsigned, b); }
; __device__ __forceinline__ float bf_lo(unsigned w) { return __uint_as_float(w << 16); }
; __device__ __forceinline__ float bf_hi(unsigned w) { return __uint_as_float(w & 0xffff0000u); }
;     __device__ __forceinline__ void operator()(f32x4 (&acc)[2][2][4][2], const Unit& u, int wr, int wc, int fr, int fq) const {
;     ...
;                 for (int bj = 0; bj < 2; ++bj) { const int c = col0 + bj * HALF;
;                     const u32x4 gb = *(const u32x4*)(Gb + (size_t)r * ldg + c);
;                     float eb[8];
; #pragma unroll
;                     for (int e = 0; e < 4; ++e) { eb[2 * e] = __builtin_amdgcn_exp2f(-1.4426950408889634f * bf_lo(gb[e])); eb[2 * e + 1] = __builtin_amdgcn_exp2f(-1.4426950408889634f * bf_hi(gb[e])); }
;                     if (u.half == 0) { const u32x4 ga = *(const u32x4*)(Ga + (size_t)r * ldg + c);
; #pragma unroll
;                         for (int e = 0; e < 4; ++e) { const float ea0 = __builtin_amdgcn_exp2f(-1.4426950408889634f * bf_lo(ga[e])), ea1 = __builtin_amdgcn_exp2f(-1.4426950408889634f * bf_hi(ga[e]));
;                             acc[ai][bj][m][e >> 1][(2 * e) & 3] *= (1.0f + eb[2 * e]) * __builtin_amdgcn_rcpf(1.0f + ea0);
;                             acc[ai][bj][m][e >> 1][(2 * e + 1) & 3] *= (1.0f + eb[2 * e + 1]) * __builtin_amdgcn_rcpf(1.0f + ea1); } }
;                     else { u32x4 w;
; #pragma unroll
;                         for (int e = 0; e < 4; ++e) { const float a0 = acc[ai][bj][m][e >> 1][(2 * e) & 3] * __builtin_amdgcn_rcpf(1.0f + eb[2 * e]), a1 = acc[ai][bj][m][e >> 1][(2 * e + 1) & 3] * __builtin_amdgcn_rcpf(1.0f + eb[2 * e + 1]);
;                             w[e] = cvt_pk_bf16(a0, a1); }
;                         *(u32x4*)(O + (size_t)r * ldo + c) = w; } } }
.LBB0_330:
	v_lshl_add_u64 v[156:157], v[2:3], 1, v[138:139]
	v_pk_add_f32 v[144:145], v[144:145], 1.0 op_sel_hi:[1,0]
	v_pk_add_f32 v[146:147], v[146:147], 1.0 op_sel_hi:[1,0]
	v_pk_add_f32 v[142:143], v[142:143], 1.0 op_sel_hi:[1,0]
	v_pk_add_f32 v[140:141], v[140:141], 1.0 op_sel_hi:[1,0]
	s_waitcnt vmcnt(4)
	v_mov_b64_e32 v[156:157], v[214:215]
	v_mov_b64_e32 v[158:159], v[216:217]
	v_lshlrev_b32_e32 v0, 16, v156
	v_mul_f32_e32 v0, 0xbfb8aa3b, v0
	v_and_b32_e32 v133, 0xffff0000, v156
	v_exp_f32_e32 v0, v0
	v_mul_f32_e32 v133, 0xbfb8aa3b, v133
	v_exp_f32_e32 v133, v133
	v_add_f32_e32 v0, 1.0, v0
	v_rcp_f32_e32 v160, v0
	v_add_f32_e32 v0, 1.0, v133
	v_rcp_f32_e32 v161, v0
	v_lshlrev_b32_e32 v0, 16, v157
	v_mul_f32_e32 v0, 0xbfb8aa3b, v0
	v_and_b32_e32 v133, 0xffff0000, v157
	v_exp_f32_e32 v0, v0
	v_mul_f32_e32 v133, 0xbfb8aa3b, v133
	v_exp_f32_e32 v133, v133
	v_pk_mul_f32 v[144:145], v[144:145], v[160:161]
	v_add_f32_e32 v0, 1.0, v0
	v_rcp_f32_e32 v156, v0
	v_add_f32_e32 v0, 1.0, v133
	v_rcp_f32_e32 v157, v0
	v_lshlrev_b32_e32 v0, 16, v158
	v_mul_f32_e32 v0, 0xbfb8aa3b, v0
	v_and_b32_e32 v133, 0xffff0000, v158
	v_exp_f32_e32 v0, v0
	v_mul_f32_e32 v133, 0xbfb8aa3b, v133
	v_exp_f32_e32 v133, v133
	v_pk_mul_f32 v[120:121], v[120:121], v[144:145]
	v_add_f32_e32 v0, 1.0, v0
	v_rcp_f32_e32 v144, v0
	v_add_f32_e32 v0, 1.0, v133
	v_rcp_f32_e32 v145, v0
	v_lshlrev_b32_e32 v0, 16, v159
	v_mul_f32_e32 v0, 0xbfb8aa3b, v0
	v_and_b32_e32 v133, 0xffff0000, v159
	v_exp_f32_e32 v0, v0
	v_mul_f32_e32 v133, 0xbfb8aa3b, v133
	v_exp_f32_e32 v133, v133
	v_pk_mul_f32 v[146:147], v[146:147], v[156:157]
	v_add_f32_e32 v0, 1.0, v0
	v_pk_mul_f32 v[122:123], v[122:123], v[146:147]
	v_rcp_f32_e32 v146, v0
	v_add_f32_e32 v0, 1.0, v133
	v_rcp_f32_e32 v147, v0
	v_pk_mul_f32 v[140:141], v[140:141], v[144:145]
	v_pk_mul_f32 v[142:143], v[142:143], v[146:147]
	s_nop 0
	v_pk_mul_f32 v[118:119], v[118:119], v[142:143]
	v_pk_mul_f32 v[116:117], v[116:117], v[140:141]
.LBB0_331:
	s_and_b64 vcc, exec, s[8:9]
	s_waitcnt vmcnt(7)
	v_mov_b64_e32 v[140:141], v[170:171]
	v_mov_b64_e32 v[142:143], v[172:173]
	v_lshlrev_b32_e32 v0, 16, v140
	v_and_b32_e32 v133, 0xffff0000, v140
	v_lshlrev_b32_e32 v136, 16, v141
	v_and_b32_e32 v137, 0xffff0000, v141
	v_lshlrev_b32_e32 v140, 16, v142
	v_and_b32_e32 v141, 0xffff0000, v142
	v_lshlrev_b32_e32 v142, 16, v143
	v_and_b32_e32 v143, 0xffff0000, v143
	v_mul_f32_e32 v0, 0xbfb8aa3b, v0
	v_mul_f32_e32 v133, 0xbfb8aa3b, v133
	v_mul_f32_e32 v136, 0xbfb8aa3b, v136
	v_mul_f32_e32 v137, 0xbfb8aa3b, v137
	v_mul_f32_e32 v140, 0xbfb8aa3b, v140
	v_mul_f32_e32 v141, 0xbfb8aa3b, v141
	v_mul_f32_e32 v146, 0xbfb8aa3b, v142
	v_mul_f32_e32 v147, 0xbfb8aa3b, v143
	v_exp_f32_e32 v142, v0
	v_exp_f32_e32 v143, v133
	v_exp_f32_e32 v144, v136
	v_exp_f32_e32 v145, v137
	v_exp_f32_e32 v136, v140
	v_exp_f32_e32 v137, v141
	v_exp_f32_e32 v140, v146
	v_exp_f32_e32 v141, v147
	s_cbranch_vccnz .LBB0_376
	v_add_f32_e32 v0, 1.0, v142
	v_rcp_f32_e32 v146, v0
	v_add_f32_e32 v0, 1.0, v143
	v_rcp_f32_e32 v147, v0
	v_add_f32_e32 v0, 1.0, v144
	v_lshl_add_u64 v[134:135], v[2:3], 1, v[134:135]
	v_pk_mul_f32 v[146:147], v[88:89], v[146:147]
	s_nop 0
	v_cvt_pk_bf16_f32 v156, v146, v147
	v_rcp_f32_e32 v146, v0
	v_add_f32_e32 v0, 1.0, v145
	v_rcp_f32_e32 v147, v0
	v_add_f32_e32 v0, 1.0, v136
	v_pk_mul_f32 v[146:147], v[90:91], v[146:147]
	s_nop 0
	v_cvt_pk_bf16_f32 v157, v146, v147
	v_rcp_f32_e32 v146, v0
	v_add_f32_e32 v0, 1.0, v137
	v_rcp_f32_e32 v147, v0
	v_add_f32_e32 v0, 1.0, v140
	v_pk_mul_f32 v[146:147], v[84:85], v[146:147]
	s_nop 0
	v_cvt_pk_bf16_f32 v158, v146, v147
	v_rcp_f32_e32 v146, v0
	v_add_f32_e32 v0, 1.0, v141
	v_rcp_f32_e32 v147, v0
	s_nop 0
	v_pk_mul_f32 v[146:147], v[86:87], v[146:147]
	s_nop 0
	v_cvt_pk_bf16_f32 v159, v146, v147
	global_store_dwordx4 v[134:135], v[156:159], off offset:256
	s_cbranch_execnz .LBB0_334
.LBB0_333:
	v_lshl_add_u64 v[134:135], v[2:3], 1, v[138:139]
	v_pk_add_f32 v[142:143], v[142:143], 1.0 op_sel_hi:[1,0]
	v_pk_add_f32 v[144:145], v[144:145], 1.0 op_sel_hi:[1,0]
	v_pk_add_f32 v[140:141], v[140:141], 1.0 op_sel_hi:[1,0]
	v_pk_add_f32 v[136:137], v[136:137], 1.0 op_sel_hi:[1,0]
	s_waitcnt vmcnt(3)
	v_mov_b64_e32 v[156:157], v[218:219]
	v_mov_b64_e32 v[158:159], v[220:221]
	v_lshlrev_b32_e32 v0, 16, v156
	v_mul_f32_e32 v0, 0xbfb8aa3b, v0
	v_and_b32_e32 v133, 0xffff0000, v156
	v_exp_f32_e32 v0, v0
	v_mul_f32_e32 v133, 0xbfb8aa3b, v133
	v_exp_f32_e32 v133, v133
	v_add_f32_e32 v0, 1.0, v0
	v_rcp_f32_e32 v134, v0
	v_add_f32_e32 v0, 1.0, v133
	v_rcp_f32_e32 v135, v0
	v_lshlrev_b32_e32 v0, 16, v157
	v_mul_f32_e32 v0, 0xbfb8aa3b, v0
	v_and_b32_e32 v133, 0xffff0000, v157
	v_exp_f32_e32 v0, v0
	v_mul_f32_e32 v133, 0xbfb8aa3b, v133
	v_exp_f32_e32 v133, v133
	v_pk_mul_f32 v[134:135], v[142:143], v[134:135]
	v_add_f32_e32 v0, 1.0, v0
	v_rcp_f32_e32 v138, v0
	v_add_f32_e32 v0, 1.0, v133
	v_rcp_f32_e32 v139, v0
	v_lshlrev_b32_e32 v0, 16, v158
	v_mul_f32_e32 v0, 0xbfb8aa3b, v0
	v_and_b32_e32 v133, 0xffff0000, v158
	v_exp_f32_e32 v0, v0
	v_mul_f32_e32 v133, 0xbfb8aa3b, v133
	v_exp_f32_e32 v133, v133
	v_pk_mul_f32 v[88:89], v[88:89], v[134:135]
	v_add_f32_e32 v0, 1.0, v0
	v_rcp_f32_e32 v134, v0
	v_add_f32_e32 v0, 1.0, v133
	v_rcp_f32_e32 v135, v0
	v_lshlrev_b32_e32 v0, 16, v159
	v_mul_f32_e32 v0, 0xbfb8aa3b, v0
	v_and_b32_e32 v133, 0xffff0000, v159
	v_exp_f32_e32 v0, v0
	v_mul_f32_e32 v133, 0xbfb8aa3b, v133
	v_exp_f32_e32 v133, v133
	v_pk_mul_f32 v[138:139], v[144:145], v[138:139]
	v_add_f32_e32 v0, 1.0, v0
	v_pk_mul_f32 v[90:91], v[90:91], v[138:139]
	v_rcp_f32_e32 v138, v0
	v_add_f32_e32 v0, 1.0, v133
	v_rcp_f32_e32 v139, v0
	v_pk_mul_f32 v[134:135], v[136:137], v[134:135]
	v_pk_mul_f32 v[136:137], v[140:141], v[138:139]
	s_nop 0
	v_pk_mul_f32 v[86:87], v[86:87], v[136:137]
	v_pk_mul_f32 v[84:85], v[84:85], v[134:135]
; __device__ __forceinline__ unsigned cvt_pk_bf16(float lo, float hi) { f32x2 v = {lo, hi}; bf16x2_t b = __builtin_convertvector(v, bf16x2_t); return __builtin_bit_cast(unsigned, b); }
; __device__ __forceinline__ float bf_lo(unsigned w) { return __uint_as_float(w << 16); }
; __device__ __forceinline__ float bf_hi(unsigned w) { return __uint_as_float(w & 0xffff0000u); }
;     __device__ __forceinline__ void operator()(f32x4 (&acc)[2][2][4][2], const Unit& u, int wr, int wc, int fr, int fq) const {
;     ...
;                 for (int bj = 0; bj < 2; ++bj) { const int c = col0 + bj * HALF;
;                     const u32x4 gb = *(const u32x4*)(Gb + (size_t)r * ldg + c);
;                     float eb[8];
; #pragma unroll
;                     for (int e = 0; e < 4; ++e) { eb[2 * e] = __builtin_amdgcn_exp2f(-1.4426950408889634f * bf_lo(gb[e])); eb[2 * e + 1] = __builtin_amdgcn_exp2f(-1.4426950408889634f * bf_hi(gb[e])); }
;                     if (u.half == 0) { const u32x4 ga = *(const u32x4*)(Ga + (size_t)r * ldg + c);
; #pragma unroll
;                         for (int e = 0; e < 4; ++e) { const float ea0 = __builtin_amdgcn_exp2f(-1.4426950408889634f * bf_lo(ga[e])), ea1 = __builtin_amdgcn_exp2f(-1.4426950408889634f * bf_hi(ga[e]));
;                             acc[ai][bj][m][e >> 1][(2 * e) & 3] *= (1.0f + eb[2 * e]) * __builtin_amdgcn_rcpf(1.0f + ea0);
;                             acc[ai][bj][m][e >> 1][(2 * e + 1) & 3] *= (1.0f + eb[2 * e + 1]) * __builtin_amdgcn_rcpf(1.0f + ea1); } }
;                     else { u32x4 w;
; #pragma unroll
;                         for (int e = 0; e < 4; ++e) { const float a0 = acc[ai][bj][m][e >> 1][(2 * e) & 3] * __builtin_amdgcn_rcpf(1.0f + eb[2 * e]), a1 = acc[ai][bj][m][e >> 1][(2 * e + 1) & 3] * __builtin_amdgcn_rcpf(1.0f + eb[2 * e + 1]);
;                             w[e] = cvt_pk_bf16(a0, a1); }
;                         *(u32x4*)(O + (size_t)r * ldo + c) = w; } } }
.LBB0_334:
	v_or_b32_e32 v134, 32, v132
	v_mad_i64_i32 v[138:139], s[26:27], v134, s90, 0
	v_lshl_add_u64 v[136:137], v[138:139], 1, s[72:73]
	v_lshl_add_u64 v[136:137], v[2:3], 1, v[136:137]
	v_ashrrev_i32_e32 v135, 31, v134
	v_lshlrev_b64 v[134:135], 11, v[134:135]
	s_and_b64 vcc, exec, s[8:9]
	v_lshl_add_u64 v[134:135], s[74:75], 0, v[134:135]
	s_waitcnt vmcnt(7)
	v_mov_b64_e32 v[140:141], v[174:175]
	v_mov_b64_e32 v[142:143], v[176:177]
	v_lshlrev_b32_e32 v0, 16, v140
	v_and_b32_e32 v133, 0xffff0000, v140
	v_lshlrev_b32_e32 v140, 16, v141
	v_and_b32_e32 v141, 0xffff0000, v141
	v_lshlrev_b32_e32 v144, 16, v142
	v_and_b32_e32 v142, 0xffff0000, v142
	v_lshlrev_b32_e32 v145, 16, v143
	v_and_b32_e32 v143, 0xffff0000, v143
	v_mul_f32_e32 v0, 0xbfb8aa3b, v0
	v_mul_f32_e32 v133, 0xbfb8aa3b, v133
	v_mul_f32_e32 v140, 0xbfb8aa3b, v140
	v_mul_f32_e32 v141, 0xbfb8aa3b, v141
	v_mul_f32_e32 v156, 0xbfb8aa3b, v144
	v_mul_f32_e32 v142, 0xbfb8aa3b, v142
	v_mul_f32_e32 v157, 0xbfb8aa3b, v145
	v_mul_f32_e32 v143, 0xbfb8aa3b, v143
	v_exp_f32_e32 v144, v0
	v_exp_f32_e32 v145, v133
	v_exp_f32_e32 v146, v140
	v_exp_f32_e32 v147, v141
	v_exp_f32_e32 v140, v156
	v_exp_f32_e32 v141, v142
	v_exp_f32_e32 v142, v157
	v_exp_f32_e32 v143, v143
	s_cbranch_vccnz .LBB0_377
	v_add_f32_e32 v0, 1.0, v144
	v_rcp_f32_e32 v156, v0
	v_add_f32_e32 v0, 1.0, v145
	v_rcp_f32_e32 v157, v0
	v_add_f32_e32 v0, 1.0, v146
	v_rcp_f32_e32 v158, v0
	v_add_f32_e32 v0, 1.0, v147
	v_rcp_f32_e32 v159, v0
	v_pk_mul_f32 v[156:157], v[112:113], v[156:157]
	v_add_f32_e32 v0, 1.0, v140
	v_cvt_pk_bf16_f32 v156, v156, v157
	v_pk_mul_f32 v[158:159], v[114:115], v[158:159]
	s_nop 0
	v_cvt_pk_bf16_f32 v157, v158, v159
	v_rcp_f32_e32 v158, v0
	v_add_f32_e32 v0, 1.0, v141
	v_rcp_f32_e32 v159, v0
	v_add_f32_e32 v0, 1.0, v142
	v_rcp_f32_e32 v160, v0
	v_add_f32_e32 v0, 1.0, v143
	v_rcp_f32_e32 v161, v0
	v_pk_mul_f32 v[158:159], v[108:109], v[158:159]
	v_pk_mul_f32 v[160:161], v[110:111], v[160:161]
	v_cvt_pk_bf16_f32 v158, v158, v159
	v_cvt_pk_bf16_f32 v159, v160, v161
	v_lshl_add_u64 v[160:161], v[2:3], 1, v[134:135]
	global_store_dwordx4 v[160:161], v[156:159], off
	v_lshl_add_u64 v[138:139], v[138:139], 1, s[70:71]
	s_cbranch_execnz .LBB0_337
.LBB0_336:
	v_lshl_add_u64 v[156:157], v[2:3], 1, v[138:139]
	v_pk_add_f32 v[144:145], v[144:145], 1.0 op_sel_hi:[1,0]
	v_pk_add_f32 v[146:147], v[146:147], 1.0 op_sel_hi:[1,0]
	v_pk_add_f32 v[142:143], v[142:143], 1.0 op_sel_hi:[1,0]
	v_pk_add_f32 v[140:141], v[140:141], 1.0 op_sel_hi:[1,0]
	s_waitcnt vmcnt(2)
	v_mov_b64_e32 v[156:157], v[222:223]
	v_mov_b64_e32 v[158:159], v[224:225]
	v_lshlrev_b32_e32 v0, 16, v156
	v_mul_f32_e32 v0, 0xbfb8aa3b, v0
	v_and_b32_e32 v133, 0xffff0000, v156
	v_exp_f32_e32 v0, v0
	v_mul_f32_e32 v133, 0xbfb8aa3b, v133
	v_exp_f32_e32 v133, v133
	v_add_f32_e32 v0, 1.0, v0
	v_rcp_f32_e32 v160, v0
	v_add_f32_e32 v0, 1.0, v133
	v_rcp_f32_e32 v161, v0
	v_lshlrev_b32_e32 v0, 16, v157
	v_mul_f32_e32 v0, 0xbfb8aa3b, v0
	v_and_b32_e32 v133, 0xffff0000, v157
	v_exp_f32_e32 v0, v0
	v_mul_f32_e32 v133, 0xbfb8aa3b, v133
	v_exp_f32_e32 v133, v133
	v_pk_mul_f32 v[144:145], v[144:145], v[160:161]
	v_add_f32_e32 v0, 1.0, v0
	v_rcp_f32_e32 v156, v0
	v_add_f32_e32 v0, 1.0, v133
	v_rcp_f32_e32 v157, v0
	v_lshlrev_b32_e32 v0, 16, v158
	v_mul_f32_e32 v0, 0xbfb8aa3b, v0
	v_and_b32_e32 v133, 0xffff0000, v158
	v_exp_f32_e32 v0, v0
	v_mul_f32_e32 v133, 0xbfb8aa3b, v133
	v_exp_f32_e32 v133, v133
	v_pk_mul_f32 v[112:113], v[112:113], v[144:145]
	v_add_f32_e32 v0, 1.0, v0
	v_rcp_f32_e32 v144, v0
	v_add_f32_e32 v0, 1.0, v133
	v_rcp_f32_e32 v145, v0
	v_lshlrev_b32_e32 v0, 16, v159
	v_mul_f32_e32 v0, 0xbfb8aa3b, v0
	v_and_b32_e32 v133, 0xffff0000, v159
	v_exp_f32_e32 v0, v0
	v_mul_f32_e32 v133, 0xbfb8aa3b, v133
	v_exp_f32_e32 v133, v133
	v_pk_mul_f32 v[146:147], v[146:147], v[156:157]
	v_add_f32_e32 v0, 1.0, v0
	v_pk_mul_f32 v[114:115], v[114:115], v[146:147]
	v_rcp_f32_e32 v146, v0
	v_add_f32_e32 v0, 1.0, v133
	v_rcp_f32_e32 v147, v0
	v_pk_mul_f32 v[140:141], v[140:141], v[144:145]
	v_pk_mul_f32 v[142:143], v[142:143], v[146:147]
	s_nop 0
	v_pk_mul_f32 v[110:111], v[110:111], v[142:143]
	v_pk_mul_f32 v[108:109], v[108:109], v[140:141]
.LBB0_337:
	s_and_b64 vcc, exec, s[8:9]
	s_waitcnt vmcnt(7)
	v_mov_b64_e32 v[140:141], v[178:179]
	v_mov_b64_e32 v[142:143], v[180:181]
	v_lshlrev_b32_e32 v0, 16, v140
	v_and_b32_e32 v133, 0xffff0000, v140
	v_lshlrev_b32_e32 v136, 16, v141
	v_and_b32_e32 v137, 0xffff0000, v141
	v_lshlrev_b32_e32 v140, 16, v142
	v_and_b32_e32 v141, 0xffff0000, v142
	v_lshlrev_b32_e32 v142, 16, v143
	v_and_b32_e32 v143, 0xffff0000, v143
	v_mul_f32_e32 v0, 0xbfb8aa3b, v0
	v_mul_f32_e32 v133, 0xbfb8aa3b, v133
	v_mul_f32_e32 v136, 0xbfb8aa3b, v136
	v_mul_f32_e32 v137, 0xbfb8aa3b, v137
	v_mul_f32_e32 v140, 0xbfb8aa3b, v140
	v_mul_f32_e32 v141, 0xbfb8aa3b, v141
	v_mul_f32_e32 v146, 0xbfb8aa3b, v142
	v_mul_f32_e32 v147, 0xbfb8aa3b, v143
	v_exp_f32_e32 v142, v0
	v_exp_f32_e32 v143, v133
	v_exp_f32_e32 v144, v136
	v_exp_f32_e32 v145, v137
	v_exp_f32_e32 v136, v140
	v_exp_f32_e32 v137, v141
	v_exp_f32_e32 v140, v146
	v_exp_f32_e32 v141, v147
	s_cbranch_vccnz .LBB0_378
	v_add_f32_e32 v0, 1.0, v142
	v_rcp_f32_e32 v146, v0
	v_add_f32_e32 v0, 1.0, v143
	v_rcp_f32_e32 v147, v0
	v_add_f32_e32 v0, 1.0, v144
	v_lshl_add_u64 v[134:135], v[2:3], 1, v[134:135]
	v_pk_mul_f32 v[146:147], v[80:81], v[146:147]
	s_nop 0
	v_cvt_pk_bf16_f32 v156, v146, v147
	v_rcp_f32_e32 v146, v0
	v_add_f32_e32 v0, 1.0, v145
	v_rcp_f32_e32 v147, v0
	v_add_f32_e32 v0, 1.0, v136
	v_pk_mul_f32 v[146:147], v[82:83], v[146:147]
	s_nop 0
	v_cvt_pk_bf16_f32 v157, v146, v147
	v_rcp_f32_e32 v146, v0
	v_add_f32_e32 v0, 1.0, v137
	v_rcp_f32_e32 v147, v0
	v_add_f32_e32 v0, 1.0, v140
	v_pk_mul_f32 v[146:147], v[76:77], v[146:147]
	s_nop 0
	v_cvt_pk_bf16_f32 v158, v146, v147
	v_rcp_f32_e32 v146, v0
	v_add_f32_e32 v0, 1.0, v141
	v_rcp_f32_e32 v147, v0
	s_nop 0
	v_pk_mul_f32 v[146:147], v[78:79], v[146:147]
	s_nop 0
	v_cvt_pk_bf16_f32 v159, v146, v147
	global_store_dwordx4 v[134:135], v[156:159], off offset:256
	s_cbranch_execnz .LBB0_340
; __device__ __forceinline__ unsigned cvt_pk_bf16(float lo, float hi) { f32x2 v = {lo, hi}; bf16x2_t b = __builtin_convertvector(v, bf16x2_t); return __builtin_bit_cast(unsigned, b); }
; __device__ __forceinline__ float bf_lo(unsigned w) { return __uint_as_float(w << 16); }
; __device__ __forceinline__ float bf_hi(unsigned w) { return __uint_as_float(w & 0xffff0000u); }
;     __device__ __forceinline__ void operator()(f32x4 (&acc)[2][2][4][2], const Unit& u, int wr, int wc, int fr, int fq) const {
;     ...
;                 for (int bj = 0; bj < 2; ++bj) { const int c = col0 + bj * HALF;
;                     const u32x4 gb = *(const u32x4*)(Gb + (size_t)r * ldg + c);
;                     float eb[8];
; #pragma unroll
;                     for (int e = 0; e < 4; ++e) { eb[2 * e] = __builtin_amdgcn_exp2f(-1.4426950408889634f * bf_lo(gb[e])); eb[2 * e + 1] = __builtin_amdgcn_exp2f(-1.4426950408889634f * bf_hi(gb[e])); }
;                     if (u.half == 0) { const u32x4 ga = *(const u32x4*)(Ga + (size_t)r * ldg + c);
; #pragma unroll
;                         for (int e = 0; e < 4; ++e) { const float ea0 = __builtin_amdgcn_exp2f(-1.4426950408889634f * bf_lo(ga[e])), ea1 = __builtin_amdgcn_exp2f(-1.4426950408889634f * bf_hi(ga[e]));
;                             acc[ai][bj][m][e >> 1][(2 * e) & 3] *= (1.0f + eb[2 * e]) * __builtin_amdgcn_rcpf(1.0f + ea0);
;                             acc[ai][bj][m][e >> 1][(2 * e + 1) & 3] *= (1.0f + eb[2 * e + 1]) * __builtin_amdgcn_rcpf(1.0f + ea1); } }
;                     else { u32x4 w;
; #pragma unroll
;                         for (int e = 0; e < 4; ++e) { const float a0 = acc[ai][bj][m][e >> 1][(2 * e) & 3] * __builtin_amdgcn_rcpf(1.0f + eb[2 * e]), a1 = acc[ai][bj][m][e >> 1][(2 * e + 1) & 3] * __builtin_amdgcn_rcpf(1.0f + eb[2 * e + 1]);
;                             w[e] = cvt_pk_bf16(a0, a1); }
;                         *(u32x4*)(O + (size_t)r * ldo + c) = w; } } }
.LBB0_339:
	v_lshl_add_u64 v[134:135], v[2:3], 1, v[138:139]
	v_pk_add_f32 v[142:143], v[142:143], 1.0 op_sel_hi:[1,0]
	v_pk_add_f32 v[144:145], v[144:145], 1.0 op_sel_hi:[1,0]
	v_pk_add_f32 v[140:141], v[140:141], 1.0 op_sel_hi:[1,0]
	v_pk_add_f32 v[136:137], v[136:137], 1.0 op_sel_hi:[1,0]
	s_waitcnt vmcnt(1)
	v_mov_b64_e32 v[156:157], v[230:231]
	v_mov_b64_e32 v[158:159], v[232:233]
	v_lshlrev_b32_e32 v0, 16, v156
	v_mul_f32_e32 v0, 0xbfb8aa3b, v0
	v_and_b32_e32 v133, 0xffff0000, v156
	v_exp_f32_e32 v0, v0
	v_mul_f32_e32 v133, 0xbfb8aa3b, v133
	v_exp_f32_e32 v133, v133
	v_add_f32_e32 v0, 1.0, v0
	v_rcp_f32_e32 v134, v0
	v_add_f32_e32 v0, 1.0, v133
	v_rcp_f32_e32 v135, v0
	v_lshlrev_b32_e32 v0, 16, v157
	v_mul_f32_e32 v0, 0xbfb8aa3b, v0
	v_and_b32_e32 v133, 0xffff0000, v157
	v_exp_f32_e32 v0, v0
	v_mul_f32_e32 v133, 0xbfb8aa3b, v133
	v_exp_f32_e32 v133, v133
	v_pk_mul_f32 v[134:135], v[142:143], v[134:135]
	v_add_f32_e32 v0, 1.0, v0
	v_rcp_f32_e32 v138, v0
	v_add_f32_e32 v0, 1.0, v133
	v_rcp_f32_e32 v139, v0
	v_lshlrev_b32_e32 v0, 16, v158
	v_mul_f32_e32 v0, 0xbfb8aa3b, v0
	v_and_b32_e32 v133, 0xffff0000, v158
	v_exp_f32_e32 v0, v0
	v_mul_f32_e32 v133, 0xbfb8aa3b, v133
	v_exp_f32_e32 v133, v133
	v_pk_mul_f32 v[80:81], v[80:81], v[134:135]
	v_add_f32_e32 v0, 1.0, v0
	v_rcp_f32_e32 v134, v0
	v_add_f32_e32 v0, 1.0, v133
	v_rcp_f32_e32 v135, v0
	v_lshlrev_b32_e32 v0, 16, v159
	v_mul_f32_e32 v0, 0xbfb8aa3b, v0
	v_and_b32_e32 v133, 0xffff0000, v159
	v_exp_f32_e32 v0, v0
	v_mul_f32_e32 v133, 0xbfb8aa3b, v133
	v_exp_f32_e32 v133, v133
	v_pk_mul_f32 v[138:139], v[144:145], v[138:139]
	v_add_f32_e32 v0, 1.0, v0
	v_pk_mul_f32 v[82:83], v[82:83], v[138:139]
	v_rcp_f32_e32 v138, v0
	v_add_f32_e32 v0, 1.0, v133
	v_rcp_f32_e32 v139, v0
	v_pk_mul_f32 v[134:135], v[136:137], v[134:135]
	v_pk_mul_f32 v[136:137], v[140:141], v[138:139]
	s_nop 0
	v_pk_mul_f32 v[78:79], v[78:79], v[136:137]
	v_pk_mul_f32 v[76:77], v[76:77], v[134:135]
.LBB0_340:
	v_or_b32_e32 v134, 48, v132
	v_mad_i64_i32 v[138:139], s[26:27], v134, s90, 0
	v_lshl_add_u64 v[136:137], v[138:139], 1, s[72:73]
	v_lshl_add_u64 v[136:137], v[2:3], 1, v[136:137]
	v_ashrrev_i32_e32 v135, 31, v134
	v_lshlrev_b64 v[134:135], 11, v[134:135]
	s_and_b64 vcc, exec, s[8:9]
	v_lshl_add_u64 v[134:135], s[74:75], 0, v[134:135]
	s_waitcnt vmcnt(7)
	v_mov_b64_e32 v[140:141], v[182:183]
	v_mov_b64_e32 v[142:143], v[184:185]
	v_lshlrev_b32_e32 v0, 16, v140
	v_and_b32_e32 v133, 0xffff0000, v140
	v_lshlrev_b32_e32 v140, 16, v141
	v_and_b32_e32 v141, 0xffff0000, v141
	v_lshlrev_b32_e32 v144, 16, v142
	v_and_b32_e32 v142, 0xffff0000, v142
	v_lshlrev_b32_e32 v145, 16, v143
	v_and_b32_e32 v143, 0xffff0000, v143
	v_mul_f32_e32 v0, 0xbfb8aa3b, v0
	v_mul_f32_e32 v133, 0xbfb8aa3b, v133
	v_mul_f32_e32 v140, 0xbfb8aa3b, v140
	v_mul_f32_e32 v141, 0xbfb8aa3b, v141
	v_mul_f32_e32 v156, 0xbfb8aa3b, v144
	v_mul_f32_e32 v142, 0xbfb8aa3b, v142
	v_mul_f32_e32 v157, 0xbfb8aa3b, v145
	v_mul_f32_e32 v143, 0xbfb8aa3b, v143
	v_exp_f32_e32 v144, v0
	v_exp_f32_e32 v145, v133
	v_exp_f32_e32 v146, v140
	v_exp_f32_e32 v147, v141
	v_exp_f32_e32 v140, v156
	v_exp_f32_e32 v141, v142
	v_exp_f32_e32 v142, v157
	v_exp_f32_e32 v143, v143
	s_cbranch_vccnz .LBB0_379
	v_add_f32_e32 v0, 1.0, v144
	v_rcp_f32_e32 v156, v0
	v_add_f32_e32 v0, 1.0, v145
	v_rcp_f32_e32 v157, v0
	v_add_f32_e32 v0, 1.0, v146
	v_rcp_f32_e32 v158, v0
	v_add_f32_e32 v0, 1.0, v147
	v_rcp_f32_e32 v159, v0
	v_pk_mul_f32 v[156:157], v[104:105], v[156:157]
	v_add_f32_e32 v0, 1.0, v140
	v_cvt_pk_bf16_f32 v156, v156, v157
	v_pk_mul_f32 v[158:159], v[106:107], v[158:159]
	s_nop 0
	v_cvt_pk_bf16_f32 v157, v158, v159
	v_rcp_f32_e32 v158, v0
	v_add_f32_e32 v0, 1.0, v141
	v_rcp_f32_e32 v159, v0
	v_add_f32_e32 v0, 1.0, v142
	v_rcp_f32_e32 v160, v0
	v_add_f32_e32 v0, 1.0, v143
	v_rcp_f32_e32 v161, v0
	v_pk_mul_f32 v[158:159], v[100:101], v[158:159]
	v_pk_mul_f32 v[160:161], v[102:103], v[160:161]
	v_cvt_pk_bf16_f32 v158, v158, v159
	v_cvt_pk_bf16_f32 v159, v160, v161
	v_lshl_add_u64 v[160:161], v[2:3], 1, v[134:135]
	global_store_dwordx4 v[160:161], v[156:159], off
	v_lshl_add_u64 v[138:139], v[138:139], 1, s[70:71]
	s_cbranch_execnz .LBB0_343
; __device__ __forceinline__ unsigned cvt_pk_bf16(float lo, float hi) { f32x2 v = {lo, hi}; bf16x2_t b = __builtin_convertvector(v, bf16x2_t); return __builtin_bit_cast(unsigned, b); }
; __device__ __forceinline__ float bf_lo(unsigned w) { return __uint_as_float(w << 16); }
; __device__ __forceinline__ float bf_hi(unsigned w) { return __uint_as_float(w & 0xffff0000u); }
;     __device__ __forceinline__ void operator()(f32x4 (&acc)[2][2][4][2], const Unit& u, int wr, int wc, int fr, int fq) const {
;     ...
;                 for (int bj = 0; bj < 2; ++bj) { const int c = col0 + bj * HALF;
;                     const u32x4 gb = *(const u32x4*)(Gb + (size_t)r * ldg + c);
;                     float eb[8];
; #pragma unroll
;                     for (int e = 0; e < 4; ++e) { eb[2 * e] = __builtin_amdgcn_exp2f(-1.4426950408889634f * bf_lo(gb[e])); eb[2 * e + 1] = __builtin_amdgcn_exp2f(-1.4426950408889634f * bf_hi(gb[e])); }
;                     if (u.half == 0) { const u32x4 ga = *(const u32x4*)(Ga + (size_t)r * ldg + c);
; #pragma unroll
;                         for (int e = 0; e < 4; ++e) { const float ea0 = __builtin_amdgcn_exp2f(-1.4426950408889634f * bf_lo(ga[e])), ea1 = __builtin_amdgcn_exp2f(-1.4426950408889634f * bf_hi(ga[e]));
;                             acc[ai][bj][m][e >> 1][(2 * e) & 3] *= (1.0f + eb[2 * e]) * __builtin_amdgcn_rcpf(1.0f + ea0);
;                             acc[ai][bj][m][e >> 1][(2 * e + 1) & 3] *= (1.0f + eb[2 * e + 1]) * __builtin_amdgcn_rcpf(1.0f + ea1); } }
;                     else { u32x4 w;
; #pragma unroll
;                         for (int e = 0; e < 4; ++e) { const float a0 = acc[ai][bj][m][e >> 1][(2 * e) & 3] * __builtin_amdgcn_rcpf(1.0f + eb[2 * e]), a1 = acc[ai][bj][m][e >> 1][(2 * e + 1) & 3] * __builtin_amdgcn_rcpf(1.0f + eb[2 * e + 1]);
;                             w[e] = cvt_pk_bf16(a0, a1); }
;                         *(u32x4*)(O + (size_t)r * ldo + c) = w; } } }
.LBB0_342:
	v_lshl_add_u64 v[156:157], v[2:3], 1, v[138:139]
	v_pk_add_f32 v[144:145], v[144:145], 1.0 op_sel_hi:[1,0]
	v_pk_add_f32 v[146:147], v[146:147], 1.0 op_sel_hi:[1,0]
	v_pk_add_f32 v[142:143], v[142:143], 1.0 op_sel_hi:[1,0]
	v_pk_add_f32 v[140:141], v[140:141], 1.0 op_sel_hi:[1,0]
	s_waitcnt vmcnt(0)
	v_mov_b64_e32 v[156:157], v[234:235]
	v_mov_b64_e32 v[158:159], v[236:237]
	v_lshlrev_b32_e32 v0, 16, v156
	v_mul_f32_e32 v0, 0xbfb8aa3b, v0
	v_and_b32_e32 v133, 0xffff0000, v156
	v_exp_f32_e32 v0, v0
	v_mul_f32_e32 v133, 0xbfb8aa3b, v133
	v_exp_f32_e32 v133, v133
	v_add_f32_e32 v0, 1.0, v0
	v_rcp_f32_e32 v160, v0
	v_add_f32_e32 v0, 1.0, v133
	v_rcp_f32_e32 v161, v0
	v_lshlrev_b32_e32 v0, 16, v157
	v_mul_f32_e32 v0, 0xbfb8aa3b, v0
	v_and_b32_e32 v133, 0xffff0000, v157
	v_exp_f32_e32 v0, v0
	v_mul_f32_e32 v133, 0xbfb8aa3b, v133
	v_exp_f32_e32 v133, v133
	v_pk_mul_f32 v[144:145], v[144:145], v[160:161]
	v_add_f32_e32 v0, 1.0, v0
	v_rcp_f32_e32 v156, v0
	v_add_f32_e32 v0, 1.0, v133
	v_rcp_f32_e32 v157, v0
	v_lshlrev_b32_e32 v0, 16, v158
	v_mul_f32_e32 v0, 0xbfb8aa3b, v0
	v_and_b32_e32 v133, 0xffff0000, v158
	v_exp_f32_e32 v0, v0
	v_mul_f32_e32 v133, 0xbfb8aa3b, v133
	v_exp_f32_e32 v133, v133
	v_pk_mul_f32 v[104:105], v[104:105], v[144:145]
	v_add_f32_e32 v0, 1.0, v0
	v_rcp_f32_e32 v144, v0
	v_add_f32_e32 v0, 1.0, v133
	v_rcp_f32_e32 v145, v0
	v_lshlrev_b32_e32 v0, 16, v159
	v_mul_f32_e32 v0, 0xbfb8aa3b, v0
	v_and_b32_e32 v133, 0xffff0000, v159
	v_exp_f32_e32 v0, v0
	v_mul_f32_e32 v133, 0xbfb8aa3b, v133
	v_exp_f32_e32 v133, v133
	v_pk_mul_f32 v[146:147], v[146:147], v[156:157]
	v_add_f32_e32 v0, 1.0, v0
	v_pk_mul_f32 v[106:107], v[106:107], v[146:147]
	v_rcp_f32_e32 v146, v0
	v_add_f32_e32 v0, 1.0, v133
	v_rcp_f32_e32 v147, v0
	v_pk_mul_f32 v[140:141], v[140:141], v[144:145]
	v_pk_mul_f32 v[142:143], v[142:143], v[146:147]
	s_nop 0
	v_pk_mul_f32 v[102:103], v[102:103], v[142:143]
	v_pk_mul_f32 v[100:101], v[100:101], v[140:141]
.LBB0_343:
	s_and_b64 vcc, exec, s[8:9]
	s_waitcnt vmcnt(7)
	v_mov_b64_e32 v[140:141], v[186:187]
	v_mov_b64_e32 v[142:143], v[188:189]
	v_lshlrev_b32_e32 v0, 16, v140
	v_and_b32_e32 v133, 0xffff0000, v140
	v_lshlrev_b32_e32 v136, 16, v141
	v_and_b32_e32 v137, 0xffff0000, v141
	v_lshlrev_b32_e32 v140, 16, v142
	v_and_b32_e32 v141, 0xffff0000, v142
	v_lshlrev_b32_e32 v142, 16, v143
	v_and_b32_e32 v143, 0xffff0000, v143
	v_mul_f32_e32 v0, 0xbfb8aa3b, v0
	v_mul_f32_e32 v133, 0xbfb8aa3b, v133
	v_mul_f32_e32 v136, 0xbfb8aa3b, v136
	v_mul_f32_e32 v137, 0xbfb8aa3b, v137
	v_mul_f32_e32 v140, 0xbfb8aa3b, v140
	v_mul_f32_e32 v141, 0xbfb8aa3b, v141
	v_mul_f32_e32 v146, 0xbfb8aa3b, v142
	v_mul_f32_e32 v147, 0xbfb8aa3b, v143
	v_exp_f32_e32 v142, v0
	v_exp_f32_e32 v143, v133
	v_exp_f32_e32 v144, v136
	v_exp_f32_e32 v145, v137
	v_exp_f32_e32 v136, v140
	v_exp_f32_e32 v137, v141
	v_exp_f32_e32 v140, v146
	v_exp_f32_e32 v141, v147
	s_cbranch_vccnz .LBB0_380
	v_add_f32_e32 v0, 1.0, v142
	v_rcp_f32_e32 v146, v0
	v_add_f32_e32 v0, 1.0, v143
	v_rcp_f32_e32 v147, v0
	v_add_f32_e32 v0, 1.0, v144
	v_lshl_add_u64 v[134:135], v[2:3], 1, v[134:135]
	v_pk_mul_f32 v[146:147], v[72:73], v[146:147]
	s_nop 0
	v_cvt_pk_bf16_f32 v156, v146, v147
	v_rcp_f32_e32 v146, v0
	v_add_f32_e32 v0, 1.0, v145
	v_rcp_f32_e32 v147, v0
	v_add_f32_e32 v0, 1.0, v136
	v_pk_mul_f32 v[146:147], v[74:75], v[146:147]
	s_nop 0
	v_cvt_pk_bf16_f32 v157, v146, v147
	v_rcp_f32_e32 v146, v0
	v_add_f32_e32 v0, 1.0, v137
	v_rcp_f32_e32 v147, v0
	v_add_f32_e32 v0, 1.0, v140
	v_pk_mul_f32 v[146:147], v[68:69], v[146:147]
	s_nop 0
	v_cvt_pk_bf16_f32 v158, v146, v147
	v_rcp_f32_e32 v146, v0
	v_add_f32_e32 v0, 1.0, v141
	v_rcp_f32_e32 v147, v0
	s_nop 0
	v_pk_mul_f32 v[146:147], v[70:71], v[146:147]
	s_nop 0
	v_cvt_pk_bf16_f32 v159, v146, v147
	global_store_dwordx4 v[134:135], v[156:159], off offset:256
	s_cbranch_execnz .LBB0_346

; __device__ __forceinline__ unsigned cvt_pk_bf16(float lo, float hi) { f32x2 v = {lo, hi}; bf16x2_t b = __builtin_convertvector(v, bf16x2_t); return __builtin_bit_cast(unsigned, b); }
; __device__ __forceinline__ float bf_lo(unsigned w) { return __uint_as_float(w << 16); }
; __device__ __forceinline__ float bf_hi(unsigned w) { return __uint_as_float(w & 0xffff0000u); }
;     __device__ __forceinline__ void operator()(f32x4 (&acc)[2][2][4][2], const Unit& u, int wr, int wc, int fr, int fq) const {
;     ...
;                 for (int bj = 0; bj < 2; ++bj) { const int c = col0 + bj * HALF;
;                     const u32x4 gb = *(const u32x4*)(Gb + (size_t)r * ldg + c);
;                     float eb[8];
; #pragma unroll
;                     for (int e = 0; e < 4; ++e) { eb[2 * e] = __builtin_amdgcn_exp2f(-1.4426950408889634f * bf_lo(gb[e])); eb[2 * e + 1] = __builtin_amdgcn_exp2f(-1.4426950408889634f * bf_hi(gb[e])); }
;                     if (u.half == 0) { const u32x4 ga = *(const u32x4*)(Ga + (size_t)r * ldg + c);
; #pragma unroll
;                         for (int e = 0; e < 4; ++e) { const float ea0 = __builtin_amdgcn_exp2f(-1.4426950408889634f * bf_lo(ga[e])), ea1 = __builtin_amdgcn_exp2f(-1.4426950408889634f * bf_hi(ga[e]));
;                             acc[ai][bj][m][e >> 1][(2 * e) & 3] *= (1.0f + eb[2 * e]) * __builtin_amdgcn_rcpf(1.0f + ea0);
;                             acc[ai][bj][m][e >> 1][(2 * e + 1) & 3] *= (1.0f + eb[2 * e + 1]) * __builtin_amdgcn_rcpf(1.0f + ea1); } }
;                     else { u32x4 w;
; #pragma unroll
;                         for (int e = 0; e < 4; ++e) { const float a0 = acc[ai][bj][m][e >> 1][(2 * e) & 3] * __builtin_amdgcn_rcpf(1.0f + eb[2 * e]), a1 = acc[ai][bj][m][e >> 1][(2 * e + 1) & 3] * __builtin_amdgcn_rcpf(1.0f + eb[2 * e + 1]);
;                             w[e] = cvt_pk_bf16(a0, a1); }
;                         *(u32x4*)(O + (size_t)r * ldo + c) = w; } } }
.LBB0_346:
	v_add_u32_e32 v134, 0x80, v132
	v_mad_i64_i32 v[138:139], s[26:27], v134, s90, 0
	v_lshl_add_u64 v[136:137], v[138:139], 1, s[72:73]
	v_lshl_add_u64 v[136:137], v[2:3], 1, v[136:137]
	global_load_dwordx4 v[140:143], v[136:137], off
	global_load_dwordx4 v[162:165], v[136:137], off offset:256
	v_add_co_u32_e32 v226, vcc, 0x48000, v136
	s_nop 1
	v_addc_co_u32_e32 v227, vcc, 0, v137, vcc
	global_load_dwordx4 v[166:169], v[226:227], off
	global_load_dwordx4 v[170:173], v[226:227], off offset:256
	v_add_co_u32_e32 v226, vcc, 0x90000, v136
	s_nop 1
	v_addc_co_u32_e32 v227, vcc, 0, v137, vcc
	global_load_dwordx4 v[174:177], v[226:227], off
	global_load_dwordx4 v[178:181], v[226:227], off offset:256
	v_add_co_u32_e32 v226, vcc, 0xd8000, v136
	s_nop 1
	v_addc_co_u32_e32 v227, vcc, 0, v137, vcc
	global_load_dwordx4 v[182:185], v[226:227], off
	global_load_dwordx4 v[186:189], v[226:227], off offset:256
	s_cmp_lg_u32 s10, 0
	s_cbranch_scc1 .Lepid_skip_B
	global_load_dwordx4 v[190:193], v[136:137], off offset:-2048
	global_load_dwordx4 v[210:213], v[136:137], off offset:-1792
	v_add_co_u32_e32 v226, vcc, 0x48000, v136
	s_nop 1
	v_addc_co_u32_e32 v227, vcc, 0, v137, vcc
	global_load_dwordx4 v[214:217], v[226:227], off offset:-2048
	global_load_dwordx4 v[218:221], v[226:227], off offset:-1792
	v_add_co_u32_e32 v226, vcc, 0x90000, v136
	s_nop 1
	v_addc_co_u32_e32 v227, vcc, 0, v137, vcc
	global_load_dwordx4 v[222:225], v[226:227], off offset:-2048
	global_load_dwordx4 v[230:233], v[226:227], off offset:-1792
	v_add_co_u32_e32 v226, vcc, 0xd8000, v136
	s_nop 1
	v_addc_co_u32_e32 v227, vcc, 0, v137, vcc
	global_load_dwordx4 v[234:237], v[226:227], off offset:-2048
	.Lepid_skip_B:
	v_ashrrev_i32_e32 v135, 31, v134
	v_lshlrev_b64 v[134:135], 11, v[134:135]
	s_and_b64 vcc, exec, s[8:9]
	v_lshl_add_u64 v[134:135], s[74:75], 0, v[134:135]
	s_waitcnt vmcnt(7)
	v_lshlrev_b32_e32 v0, 16, v140
	v_and_b32_e32 v133, 0xffff0000, v140
	v_lshlrev_b32_e32 v140, 16, v141
	v_and_b32_e32 v141, 0xffff0000, v141
	v_lshlrev_b32_e32 v144, 16, v142
	v_and_b32_e32 v142, 0xffff0000, v142
	v_lshlrev_b32_e32 v145, 16, v143
	v_and_b32_e32 v143, 0xffff0000, v143
	v_mul_f32_e32 v0, 0xbfb8aa3b, v0
	v_mul_f32_e32 v133, 0xbfb8aa3b, v133
	v_mul_f32_e32 v140, 0xbfb8aa3b, v140
	v_mul_f32_e32 v141, 0xbfb8aa3b, v141
	v_mul_f32_e32 v156, 0xbfb8aa3b, v144
	v_mul_f32_e32 v142, 0xbfb8aa3b, v142
	v_mul_f32_e32 v157, 0xbfb8aa3b, v145
	v_mul_f32_e32 v143, 0xbfb8aa3b, v143
	v_exp_f32_e32 v144, v0
	v_exp_f32_e32 v145, v133
	v_exp_f32_e32 v146, v140
	v_exp_f32_e32 v147, v141
	v_exp_f32_e32 v140, v156
	v_exp_f32_e32 v141, v142
	v_exp_f32_e32 v142, v157
	v_exp_f32_e32 v143, v143
	s_cbranch_vccnz .LBB0_381
	v_add_f32_e32 v0, 1.0, v144
	v_rcp_f32_e32 v156, v0
	v_add_f32_e32 v0, 1.0, v145
	v_rcp_f32_e32 v157, v0
	v_add_f32_e32 v0, 1.0, v146
	v_rcp_f32_e32 v158, v0
	v_add_f32_e32 v0, 1.0, v147
	v_rcp_f32_e32 v159, v0
	v_pk_mul_f32 v[156:157], v[64:65], v[156:157]
	v_add_f32_e32 v0, 1.0, v140
	v_cvt_pk_bf16_f32 v156, v156, v157
	v_pk_mul_f32 v[158:159], v[66:67], v[158:159]
	s_nop 0
	v_cvt_pk_bf16_f32 v157, v158, v159
	v_rcp_f32_e32 v158, v0
	v_add_f32_e32 v0, 1.0, v141
	v_rcp_f32_e32 v159, v0
	v_add_f32_e32 v0, 1.0, v142
	v_rcp_f32_e32 v160, v0
	v_add_f32_e32 v0, 1.0, v143
	v_rcp_f32_e32 v161, v0
	v_pk_mul_f32 v[158:159], v[60:61], v[158:159]
	v_pk_mul_f32 v[160:161], v[62:63], v[160:161]
	v_cvt_pk_bf16_f32 v158, v158, v159
	v_cvt_pk_bf16_f32 v159, v160, v161
	v_lshl_add_u64 v[160:161], v[2:3], 1, v[134:135]
	global_store_dwordx4 v[160:161], v[156:159], off
	v_lshl_add_u64 v[138:139], v[138:139], 1, s[70:71]
	s_cbranch_execnz .LBB0_349
.LBB0_348:
	v_lshl_add_u64 v[156:157], v[2:3], 1, v[138:139]
	v_pk_add_f32 v[144:145], v[144:145], 1.0 op_sel_hi:[1,0]
	v_pk_add_f32 v[146:147], v[146:147], 1.0 op_sel_hi:[1,0]
	v_pk_add_f32 v[142:143], v[142:143], 1.0 op_sel_hi:[1,0]
	v_pk_add_f32 v[140:141], v[140:141], 1.0 op_sel_hi:[1,0]
	s_waitcnt vmcnt(6)
	v_mov_b64_e32 v[156:157], v[190:191]
	v_mov_b64_e32 v[158:159], v[192:193]
	v_lshlrev_b32_e32 v0, 16, v156
	v_mul_f32_e32 v0, 0xbfb8aa3b, v0
	v_and_b32_e32 v133, 0xffff0000, v156
	v_exp_f32_e32 v0, v0
	v_mul_f32_e32 v133, 0xbfb8aa3b, v133
	v_exp_f32_e32 v133, v133
	v_add_f32_e32 v0, 1.0, v0
	v_rcp_f32_e32 v160, v0
	v_add_f32_e32 v0, 1.0, v133
	v_rcp_f32_e32 v161, v0
	v_lshlrev_b32_e32 v0, 16, v157
	v_mul_f32_e32 v0, 0xbfb8aa3b, v0
	v_and_b32_e32 v133, 0xffff0000, v157
	v_exp_f32_e32 v0, v0
	v_mul_f32_e32 v133, 0xbfb8aa3b, v133
	v_exp_f32_e32 v133, v133
	v_pk_mul_f32 v[144:145], v[144:145], v[160:161]
	v_add_f32_e32 v0, 1.0, v0
	v_rcp_f32_e32 v156, v0
	v_add_f32_e32 v0, 1.0, v133
	v_rcp_f32_e32 v157, v0
	v_lshlrev_b32_e32 v0, 16, v158
	v_mul_f32_e32 v0, 0xbfb8aa3b, v0
	v_and_b32_e32 v133, 0xffff0000, v158
	v_exp_f32_e32 v0, v0
	v_mul_f32_e32 v133, 0xbfb8aa3b, v133
	v_exp_f32_e32 v133, v133
	v_pk_mul_f32 v[64:65], v[64:65], v[144:145]
	v_add_f32_e32 v0, 1.0, v0
	v_rcp_f32_e32 v144, v0
	v_add_f32_e32 v0, 1.0, v133
	v_rcp_f32_e32 v145, v0
	v_lshlrev_b32_e32 v0, 16, v159
	v_mul_f32_e32 v0, 0xbfb8aa3b, v0
	v_and_b32_e32 v133, 0xffff0000, v159
	v_exp_f32_e32 v0, v0
	v_mul_f32_e32 v133, 0xbfb8aa3b, v133
	v_exp_f32_e32 v133, v133
	v_pk_mul_f32 v[146:147], v[146:147], v[156:157]
	v_add_f32_e32 v0, 1.0, v0
	v_pk_mul_f32 v[66:67], v[66:67], v[146:147]
	v_rcp_f32_e32 v146, v0
	v_add_f32_e32 v0, 1.0, v133
	v_rcp_f32_e32 v147, v0
	v_pk_mul_f32 v[140:141], v[140:141], v[144:145]
	v_pk_mul_f32 v[142:143], v[142:143], v[146:147]
	s_nop 0
	v_pk_mul_f32 v[62:63], v[62:63], v[142:143]
	v_pk_mul_f32 v[60:61], v[60:61], v[140:141]
; __device__ __forceinline__ unsigned cvt_pk_bf16(float lo, float hi) { f32x2 v = {lo, hi}; bf16x2_t b = __builtin_convertvector(v, bf16x2_t); return __builtin_bit_cast(unsigned, b); }
; __device__ __forceinline__ float bf_lo(unsigned w) { return __uint_as_float(w << 16); }
; __device__ __forceinline__ float bf_hi(unsigned w) { return __uint_as_float(w & 0xffff0000u); }
;     __device__ __forceinline__ void operator()(f32x4 (&acc)[2][2][4][2], const Unit& u, int wr, int wc, int fr, int fq) const {
;     ...
;             for (int m = 0; m < 4; ++m) { const int r = row0 + ai * HALF + m * 16;
; #pragma unroll
;                 for (int bj = 0; bj < 2; ++bj) { const int c = col0 + bj * HALF;
;                     const u32x4 gb = *(const u32x4*)(Gb + (size_t)r * ldg + c);
;                     float eb[8];
; #pragma unroll
;                     for (int e = 0; e < 4; ++e) { eb[2 * e] = __builtin_amdgcn_exp2f(-1.4426950408889634f * bf_lo(gb[e])); eb[2 * e + 1] = __builtin_amdgcn_exp2f(-1.4426950408889634f * bf_hi(gb[e])); }
;                     if (u.half == 0) { const u32x4 ga = *(const u32x4*)(Ga + (size_t)r * ldg + c);
; #pragma unroll
;                         for (int e = 0; e < 4; ++e) { const float ea0 = __builtin_amdgcn_exp2f(-1.4426950408889634f * bf_lo(ga[e])), ea1 = __builtin_amdgcn_exp2f(-1.4426950408889634f * bf_hi(ga[e]));
;                             acc[ai][bj][m][e >> 1][(2 * e) & 3] *= (1.0f + eb[2 * e]) * __builtin_amdgcn_rcpf(1.0f + ea0);
;                             acc[ai][bj][m][e >> 1][(2 * e + 1) & 3] *= (1.0f + eb[2 * e + 1]) * __builtin_amdgcn_rcpf(1.0f + ea1); } }
;                     else { u32x4 w;
; #pragma unroll
;                         for (int e = 0; e < 4; ++e) { const float a0 = acc[ai][bj][m][e >> 1][(2 * e) & 3] * __builtin_amdgcn_rcpf(1.0f + eb[2 * e]), a1 = acc[ai][bj][m][e >> 1][(2 * e + 1) & 3] * __builtin_amdgcn_rcpf(1.0f + eb[2 * e + 1]);
;                             w[e] = cvt_pk_bf16(a0, a1); }
;                         *(u32x4*)(O + (size_t)r * ldo + c) = w; } } }
.LBB0_349:
	s_and_b64 vcc, exec, s[8:9]
	s_waitcnt vmcnt(7)
	v_mov_b64_e32 v[140:141], v[162:163]
	v_mov_b64_e32 v[142:143], v[164:165]
	v_lshlrev_b32_e32 v0, 16, v140
	v_and_b32_e32 v133, 0xffff0000, v140
	v_lshlrev_b32_e32 v136, 16, v141
	v_and_b32_e32 v137, 0xffff0000, v141
	v_lshlrev_b32_e32 v140, 16, v142
	v_and_b32_e32 v141, 0xffff0000, v142
	v_lshlrev_b32_e32 v142, 16, v143
	v_and_b32_e32 v143, 0xffff0000, v143
	v_mul_f32_e32 v0, 0xbfb8aa3b, v0
	v_mul_f32_e32 v133, 0xbfb8aa3b, v133
	v_mul_f32_e32 v136, 0xbfb8aa3b, v136
	v_mul_f32_e32 v137, 0xbfb8aa3b, v137
	v_mul_f32_e32 v140, 0xbfb8aa3b, v140
	v_mul_f32_e32 v141, 0xbfb8aa3b, v141
	v_mul_f32_e32 v146, 0xbfb8aa3b, v142
	v_mul_f32_e32 v147, 0xbfb8aa3b, v143
	v_exp_f32_e32 v142, v0
	v_exp_f32_e32 v143, v133
	v_exp_f32_e32 v144, v136
	v_exp_f32_e32 v145, v137
	v_exp_f32_e32 v136, v140
	v_exp_f32_e32 v137, v141
	v_exp_f32_e32 v140, v146
	v_exp_f32_e32 v141, v147
	s_cbranch_vccnz .LBB0_382
	v_add_f32_e32 v0, 1.0, v142
	v_rcp_f32_e32 v146, v0
	v_add_f32_e32 v0, 1.0, v143
	v_rcp_f32_e32 v147, v0
	v_add_f32_e32 v0, 1.0, v144
	v_lshl_add_u64 v[134:135], v[2:3], 1, v[134:135]
	v_pk_mul_f32 v[146:147], v[32:33], v[146:147]
	s_nop 0
	v_cvt_pk_bf16_f32 v156, v146, v147
	v_rcp_f32_e32 v146, v0
	v_add_f32_e32 v0, 1.0, v145
	v_rcp_f32_e32 v147, v0
	v_add_f32_e32 v0, 1.0, v136
	v_pk_mul_f32 v[146:147], v[34:35], v[146:147]
	s_nop 0
	v_cvt_pk_bf16_f32 v157, v146, v147
	v_rcp_f32_e32 v146, v0
	v_add_f32_e32 v0, 1.0, v137
	v_rcp_f32_e32 v147, v0
	v_add_f32_e32 v0, 1.0, v140
	v_pk_mul_f32 v[146:147], v[28:29], v[146:147]
	s_nop 0
	v_cvt_pk_bf16_f32 v158, v146, v147
	v_rcp_f32_e32 v146, v0
	v_add_f32_e32 v0, 1.0, v141
	v_rcp_f32_e32 v147, v0
	s_nop 0
	v_pk_mul_f32 v[146:147], v[30:31], v[146:147]
	s_nop 0
	v_cvt_pk_bf16_f32 v159, v146, v147
	global_store_dwordx4 v[134:135], v[156:159], off offset:256
	s_cbranch_execnz .LBB0_352
.LBB0_351:
	v_lshl_add_u64 v[134:135], v[2:3], 1, v[138:139]
	v_pk_add_f32 v[142:143], v[142:143], 1.0 op_sel_hi:[1,0]
	v_pk_add_f32 v[144:145], v[144:145], 1.0 op_sel_hi:[1,0]
	v_pk_add_f32 v[140:141], v[140:141], 1.0 op_sel_hi:[1,0]
	v_pk_add_f32 v[136:137], v[136:137], 1.0 op_sel_hi:[1,0]
	s_waitcnt vmcnt(5)
	v_mov_b64_e32 v[156:157], v[210:211]
	v_mov_b64_e32 v[158:159], v[212:213]
	v_lshlrev_b32_e32 v0, 16, v156
	v_mul_f32_e32 v0, 0xbfb8aa3b, v0
	v_and_b32_e32 v133, 0xffff0000, v156
	v_exp_f32_e32 v0, v0
	v_mul_f32_e32 v133, 0xbfb8aa3b, v133
	v_exp_f32_e32 v133, v133
	v_add_f32_e32 v0, 1.0, v0
	v_rcp_f32_e32 v134, v0
	v_add_f32_e32 v0, 1.0, v133
	v_rcp_f32_e32 v135, v0
	v_lshlrev_b32_e32 v0, 16, v157
	v_mul_f32_e32 v0, 0xbfb8aa3b, v0
	v_and_b32_e32 v133, 0xffff0000, v157
	v_exp_f32_e32 v0, v0
	v_mul_f32_e32 v133, 0xbfb8aa3b, v133
	v_exp_f32_e32 v133, v133
	v_pk_mul_f32 v[134:135], v[142:143], v[134:135]
	v_add_f32_e32 v0, 1.0, v0
	v_rcp_f32_e32 v138, v0
	v_add_f32_e32 v0, 1.0, v133
	v_rcp_f32_e32 v139, v0
	v_lshlrev_b32_e32 v0, 16, v158
	v_mul_f32_e32 v0, 0xbfb8aa3b, v0
	v_and_b32_e32 v133, 0xffff0000, v158
	v_exp_f32_e32 v0, v0
	v_mul_f32_e32 v133, 0xbfb8aa3b, v133
	v_exp_f32_e32 v133, v133
	v_pk_mul_f32 v[32:33], v[32:33], v[134:135]
	v_add_f32_e32 v0, 1.0, v0
	v_rcp_f32_e32 v134, v0
	v_add_f32_e32 v0, 1.0, v133
	v_rcp_f32_e32 v135, v0
	v_lshlrev_b32_e32 v0, 16, v159
	v_mul_f32_e32 v0, 0xbfb8aa3b, v0
	v_and_b32_e32 v133, 0xffff0000, v159
	v_exp_f32_e32 v0, v0
	v_mul_f32_e32 v133, 0xbfb8aa3b, v133
	v_exp_f32_e32 v133, v133
	v_pk_mul_f32 v[138:139], v[144:145], v[138:139]
	v_add_f32_e32 v0, 1.0, v0
	v_pk_mul_f32 v[34:35], v[34:35], v[138:139]
	v_rcp_f32_e32 v138, v0
	v_add_f32_e32 v0, 1.0, v133
	v_rcp_f32_e32 v139, v0
	v_pk_mul_f32 v[134:135], v[136:137], v[134:135]
	v_pk_mul_f32 v[136:137], v[140:141], v[138:139]
	s_nop 0
	v_pk_mul_f32 v[30:31], v[30:31], v[136:137]
	v_pk_mul_f32 v[28:29], v[28:29], v[134:135]
.LBB0_352:
	v_add_u32_e32 v134, 0x90, v132
	v_mad_i64_i32 v[138:139], s[26:27], v134, s90, 0
	v_lshl_add_u64 v[136:137], v[138:139], 1, s[72:73]
	v_lshl_add_u64 v[136:137], v[2:3], 1, v[136:137]
	v_ashrrev_i32_e32 v135, 31, v134
	v_lshlrev_b64 v[134:135], 11, v[134:135]
	s_and_b64 vcc, exec, s[8:9]
	v_lshl_add_u64 v[134:135], s[74:75], 0, v[134:135]
	s_waitcnt vmcnt(7)
	v_mov_b64_e32 v[140:141], v[166:167]
	v_mov_b64_e32 v[142:143], v[168:169]
	v_lshlrev_b32_e32 v0, 16, v140
	v_and_b32_e32 v133, 0xffff0000, v140
	v_lshlrev_b32_e32 v140, 16, v141
	v_and_b32_e32 v141, 0xffff0000, v141
	v_lshlrev_b32_e32 v144, 16, v142
	v_and_b32_e32 v142, 0xffff0000, v142
	v_lshlrev_b32_e32 v145, 16, v143
	v_and_b32_e32 v143, 0xffff0000, v143
	v_mul_f32_e32 v0, 0xbfb8aa3b, v0
	v_mul_f32_e32 v133, 0xbfb8aa3b, v133
	v_mul_f32_e32 v140, 0xbfb8aa3b, v140
	v_mul_f32_e32 v141, 0xbfb8aa3b, v141
	v_mul_f32_e32 v156, 0xbfb8aa3b, v144
	v_mul_f32_e32 v142, 0xbfb8aa3b, v142
	v_mul_f32_e32 v157, 0xbfb8aa3b, v145
	v_mul_f32_e32 v143, 0xbfb8aa3b, v143
	v_exp_f32_e32 v144, v0
	v_exp_f32_e32 v145, v133
	v_exp_f32_e32 v146, v140
	v_exp_f32_e32 v147, v141
	v_exp_f32_e32 v140, v156
	v_exp_f32_e32 v141, v142
	v_exp_f32_e32 v142, v157
	v_exp_f32_e32 v143, v143
	s_cbranch_vccnz .LBB0_383
	v_add_f32_e32 v0, 1.0, v144
	v_rcp_f32_e32 v156, v0
	v_add_f32_e32 v0, 1.0, v145
	v_rcp_f32_e32 v157, v0
	v_add_f32_e32 v0, 1.0, v146
	v_rcp_f32_e32 v158, v0
	v_add_f32_e32 v0, 1.0, v147
	v_rcp_f32_e32 v159, v0
	v_pk_mul_f32 v[156:157], v[56:57], v[156:157]
	v_add_f32_e32 v0, 1.0, v140
	v_cvt_pk_bf16_f32 v156, v156, v157
	v_pk_mul_f32 v[158:159], v[58:59], v[158:159]
	s_nop 0
	v_cvt_pk_bf16_f32 v157, v158, v159
	v_rcp_f32_e32 v158, v0
	v_add_f32_e32 v0, 1.0, v141
	v_rcp_f32_e32 v159, v0
	v_add_f32_e32 v0, 1.0, v142
	v_rcp_f32_e32 v160, v0
	v_add_f32_e32 v0, 1.0, v143
	v_rcp_f32_e32 v161, v0
	v_pk_mul_f32 v[158:159], v[52:53], v[158:159]
	v_pk_mul_f32 v[160:161], v[54:55], v[160:161]
	v_cvt_pk_bf16_f32 v158, v158, v159
	v_cvt_pk_bf16_f32 v159, v160, v161
	v_lshl_add_u64 v[160:161], v[2:3], 1, v[134:135]
	global_store_dwordx4 v[160:161], v[156:159], off
	v_lshl_add_u64 v[138:139], v[138:139], 1, s[70:71]
	s_cbranch_execnz .LBB0_355
; __device__ __forceinline__ unsigned cvt_pk_bf16(float lo, float hi) { f32x2 v = {lo, hi}; bf16x2_t b = __builtin_convertvector(v, bf16x2_t); return __builtin_bit_cast(unsigned, b); }
; __device__ __forceinline__ float bf_lo(unsigned w) { return __uint_as_float(w << 16); }
; __device__ __forceinline__ float bf_hi(unsigned w) { return __uint_as_float(w & 0xffff0000u); }
;     __device__ __forceinline__ void operator()(f32x4 (&acc)[2][2][4][2], const Unit& u, int wr, int wc, int fr, int fq) const {
;     ...
;             for (int m = 0; m < 4; ++m) { const int r = row0 + ai * HALF + m * 16;
; #pragma unroll
;                 for (int bj = 0; bj < 2; ++bj) { const int c = col0 + bj * HALF;
;                     const u32x4 gb = *(const u32x4*)(Gb + (size_t)r * ldg + c);
;                     float eb[8];
; #pragma unroll
;                     for (int e = 0; e < 4; ++e) { eb[2 * e] = __builtin_amdgcn_exp2f(-1.4426950408889634f * bf_lo(gb[e])); eb[2 * e + 1] = __builtin_amdgcn_exp2f(-1.4426950408889634f * bf_hi(gb[e])); }
;                     if (u.half == 0) { const u32x4 ga = *(const u32x4*)(Ga + (size_t)r * ldg + c);
; #pragma unroll
;                         for (int e = 0; e < 4; ++e) { const float ea0 = __builtin_amdgcn_exp2f(-1.4426950408889634f * bf_lo(ga[e])), ea1 = __builtin_amdgcn_exp2f(-1.4426950408889634f * bf_hi(ga[e]));
;                             acc[ai][bj][m][e >> 1][(2 * e) & 3] *= (1.0f + eb[2 * e]) * __builtin_amdgcn_rcpf(1.0f + ea0);
;                             acc[ai][bj][m][e >> 1][(2 * e + 1) & 3] *= (1.0f + eb[2 * e + 1]) * __builtin_amdgcn_rcpf(1.0f + ea1); } }
;                     else { u32x4 w;
; #pragma unroll
;                         for (int e = 0; e < 4; ++e) { const float a0 = acc[ai][bj][m][e >> 1][(2 * e) & 3] * __builtin_amdgcn_rcpf(1.0f + eb[2 * e]), a1 = acc[ai][bj][m][e >> 1][(2 * e + 1) & 3] * __builtin_amdgcn_rcpf(1.0f + eb[2 * e + 1]);
;                             w[e] = cvt_pk_bf16(a0, a1); }
;                         *(u32x4*)(O + (size_t)r * ldo + c) = w; } } }
.LBB0_354:
	v_lshl_add_u64 v[156:157], v[2:3], 1, v[138:139]
	v_pk_add_f32 v[144:145], v[144:145], 1.0 op_sel_hi:[1,0]
	v_pk_add_f32 v[146:147], v[146:147], 1.0 op_sel_hi:[1,0]
	v_pk_add_f32 v[142:143], v[142:143], 1.0 op_sel_hi:[1,0]
	v_pk_add_f32 v[140:141], v[140:141], 1.0 op_sel_hi:[1,0]
	s_waitcnt vmcnt(4)
	v_mov_b64_e32 v[156:157], v[214:215]
	v_mov_b64_e32 v[158:159], v[216:217]
	v_lshlrev_b32_e32 v0, 16, v156
	v_mul_f32_e32 v0, 0xbfb8aa3b, v0
	v_and_b32_e32 v133, 0xffff0000, v156
	v_exp_f32_e32 v0, v0
	v_mul_f32_e32 v133, 0xbfb8aa3b, v133
	v_exp_f32_e32 v133, v133
	v_add_f32_e32 v0, 1.0, v0
	v_rcp_f32_e32 v160, v0
	v_add_f32_e32 v0, 1.0, v133
	v_rcp_f32_e32 v161, v0
	v_lshlrev_b32_e32 v0, 16, v157
	v_mul_f32_e32 v0, 0xbfb8aa3b, v0
	v_and_b32_e32 v133, 0xffff0000, v157
	v_exp_f32_e32 v0, v0
	v_mul_f32_e32 v133, 0xbfb8aa3b, v133
	v_exp_f32_e32 v133, v133
	v_pk_mul_f32 v[144:145], v[144:145], v[160:161]
	v_add_f32_e32 v0, 1.0, v0
	v_rcp_f32_e32 v156, v0
	v_add_f32_e32 v0, 1.0, v133
	v_rcp_f32_e32 v157, v0
	v_lshlrev_b32_e32 v0, 16, v158
	v_mul_f32_e32 v0, 0xbfb8aa3b, v0
	v_and_b32_e32 v133, 0xffff0000, v158
	v_exp_f32_e32 v0, v0
	v_mul_f32_e32 v133, 0xbfb8aa3b, v133
	v_exp_f32_e32 v133, v133
	v_pk_mul_f32 v[56:57], v[56:57], v[144:145]
	v_add_f32_e32 v0, 1.0, v0
	v_rcp_f32_e32 v144, v0
	v_add_f32_e32 v0, 1.0, v133
	v_rcp_f32_e32 v145, v0
	v_lshlrev_b32_e32 v0, 16, v159
	v_mul_f32_e32 v0, 0xbfb8aa3b, v0
	v_and_b32_e32 v133, 0xffff0000, v159
	v_exp_f32_e32 v0, v0
	v_mul_f32_e32 v133, 0xbfb8aa3b, v133
	v_exp_f32_e32 v133, v133
	v_pk_mul_f32 v[146:147], v[146:147], v[156:157]
	v_add_f32_e32 v0, 1.0, v0
	v_pk_mul_f32 v[58:59], v[58:59], v[146:147]
	v_rcp_f32_e32 v146, v0
	v_add_f32_e32 v0, 1.0, v133
	v_rcp_f32_e32 v147, v0
	v_pk_mul_f32 v[140:141], v[140:141], v[144:145]
	v_pk_mul_f32 v[142:143], v[142:143], v[146:147]
	s_nop 0
	v_pk_mul_f32 v[54:55], v[54:55], v[142:143]
	v_pk_mul_f32 v[52:53], v[52:53], v[140:141]
.LBB0_355:
	s_and_b64 vcc, exec, s[8:9]
	s_waitcnt vmcnt(7)
	v_mov_b64_e32 v[140:141], v[170:171]
	v_mov_b64_e32 v[142:143], v[172:173]
	v_lshlrev_b32_e32 v0, 16, v140
	v_and_b32_e32 v133, 0xffff0000, v140
	v_lshlrev_b32_e32 v136, 16, v141
	v_and_b32_e32 v137, 0xffff0000, v141
	v_lshlrev_b32_e32 v140, 16, v142
	v_and_b32_e32 v141, 0xffff0000, v142
	v_lshlrev_b32_e32 v142, 16, v143
	v_and_b32_e32 v143, 0xffff0000, v143
	v_mul_f32_e32 v0, 0xbfb8aa3b, v0
	v_mul_f32_e32 v133, 0xbfb8aa3b, v133
	v_mul_f32_e32 v136, 0xbfb8aa3b, v136
	v_mul_f32_e32 v137, 0xbfb8aa3b, v137
	v_mul_f32_e32 v140, 0xbfb8aa3b, v140
	v_mul_f32_e32 v141, 0xbfb8aa3b, v141
	v_mul_f32_e32 v146, 0xbfb8aa3b, v142
	v_mul_f32_e32 v147, 0xbfb8aa3b, v143
	v_exp_f32_e32 v142, v0
	v_exp_f32_e32 v143, v133
	v_exp_f32_e32 v144, v136
	v_exp_f32_e32 v145, v137
	v_exp_f32_e32 v136, v140
	v_exp_f32_e32 v137, v141
	v_exp_f32_e32 v140, v146
	v_exp_f32_e32 v141, v147
	s_cbranch_vccnz .LBB0_384
	v_add_f32_e32 v0, 1.0, v142
	v_rcp_f32_e32 v146, v0
	v_add_f32_e32 v0, 1.0, v143
	v_rcp_f32_e32 v147, v0
	v_add_f32_e32 v0, 1.0, v144
	v_lshl_add_u64 v[134:135], v[2:3], 1, v[134:135]
	v_pk_mul_f32 v[146:147], v[24:25], v[146:147]
	s_nop 0
	v_cvt_pk_bf16_f32 v156, v146, v147
	v_rcp_f32_e32 v146, v0
	v_add_f32_e32 v0, 1.0, v145
	v_rcp_f32_e32 v147, v0
	v_add_f32_e32 v0, 1.0, v136
	v_pk_mul_f32 v[146:147], v[26:27], v[146:147]
	s_nop 0
	v_cvt_pk_bf16_f32 v157, v146, v147
	v_rcp_f32_e32 v146, v0
	v_add_f32_e32 v0, 1.0, v137
	v_rcp_f32_e32 v147, v0
	v_add_f32_e32 v0, 1.0, v140
	v_pk_mul_f32 v[146:147], v[20:21], v[146:147]
	s_nop 0
	v_cvt_pk_bf16_f32 v158, v146, v147
	v_rcp_f32_e32 v146, v0
	v_add_f32_e32 v0, 1.0, v141
	v_rcp_f32_e32 v147, v0
	s_nop 0
	v_pk_mul_f32 v[146:147], v[22:23], v[146:147]
	s_nop 0
	v_cvt_pk_bf16_f32 v159, v146, v147
	global_store_dwordx4 v[134:135], v[156:159], off offset:256
	s_cbranch_execnz .LBB0_358
.LBB0_357:
	v_lshl_add_u64 v[134:135], v[2:3], 1, v[138:139]
	v_pk_add_f32 v[142:143], v[142:143], 1.0 op_sel_hi:[1,0]
	v_pk_add_f32 v[144:145], v[144:145], 1.0 op_sel_hi:[1,0]
	v_pk_add_f32 v[140:141], v[140:141], 1.0 op_sel_hi:[1,0]
	v_pk_add_f32 v[136:137], v[136:137], 1.0 op_sel_hi:[1,0]
	s_waitcnt vmcnt(3)
	v_mov_b64_e32 v[156:157], v[218:219]
	v_mov_b64_e32 v[158:159], v[220:221]
	v_lshlrev_b32_e32 v0, 16, v156
	v_mul_f32_e32 v0, 0xbfb8aa3b, v0
	v_and_b32_e32 v133, 0xffff0000, v156
	v_exp_f32_e32 v0, v0
	v_mul_f32_e32 v133, 0xbfb8aa3b, v133
	v_exp_f32_e32 v133, v133
	v_add_f32_e32 v0, 1.0, v0
	v_rcp_f32_e32 v134, v0
	v_add_f32_e32 v0, 1.0, v133
	v_rcp_f32_e32 v135, v0
	v_lshlrev_b32_e32 v0, 16, v157
	v_mul_f32_e32 v0, 0xbfb8aa3b, v0
	v_and_b32_e32 v133, 0xffff0000, v157
	v_exp_f32_e32 v0, v0
	v_mul_f32_e32 v133, 0xbfb8aa3b, v133
	v_exp_f32_e32 v133, v133
	v_pk_mul_f32 v[134:135], v[142:143], v[134:135]
	v_add_f32_e32 v0, 1.0, v0
	v_rcp_f32_e32 v138, v0
	v_add_f32_e32 v0, 1.0, v133
	v_rcp_f32_e32 v139, v0
	v_lshlrev_b32_e32 v0, 16, v158
	v_mul_f32_e32 v0, 0xbfb8aa3b, v0
	v_and_b32_e32 v133, 0xffff0000, v158
	v_exp_f32_e32 v0, v0
	v_mul_f32_e32 v133, 0xbfb8aa3b, v133
	v_exp_f32_e32 v133, v133
	v_pk_mul_f32 v[24:25], v[24:25], v[134:135]
	v_add_f32_e32 v0, 1.0, v0
	v_rcp_f32_e32 v134, v0
	v_add_f32_e32 v0, 1.0, v133
	v_rcp_f32_e32 v135, v0
	v_lshlrev_b32_e32 v0, 16, v159
	v_mul_f32_e32 v0, 0xbfb8aa3b, v0
	v_and_b32_e32 v133, 0xffff0000, v159
	v_exp_f32_e32 v0, v0
	v_mul_f32_e32 v133, 0xbfb8aa3b, v133
	v_exp_f32_e32 v133, v133
	v_pk_mul_f32 v[138:139], v[144:145], v[138:139]
	v_add_f32_e32 v0, 1.0, v0
	v_pk_mul_f32 v[26:27], v[26:27], v[138:139]
	v_rcp_f32_e32 v138, v0
	v_add_f32_e32 v0, 1.0, v133
	v_rcp_f32_e32 v139, v0
	v_pk_mul_f32 v[134:135], v[136:137], v[134:135]
	v_pk_mul_f32 v[136:137], v[140:141], v[138:139]
	s_nop 0
	v_pk_mul_f32 v[22:23], v[22:23], v[136:137]
	v_pk_mul_f32 v[20:21], v[20:21], v[134:135]
; __device__ __forceinline__ unsigned cvt_pk_bf16(float lo, float hi) { f32x2 v = {lo, hi}; bf16x2_t b = __builtin_convertvector(v, bf16x2_t); return __builtin_bit_cast(unsigned, b); }
; __device__ __forceinline__ float bf_lo(unsigned w) { return __uint_as_float(w << 16); }
; __device__ __forceinline__ float bf_hi(unsigned w) { return __uint_as_float(w & 0xffff0000u); }
;     __device__ __forceinline__ void operator()(f32x4 (&acc)[2][2][4][2], const Unit& u, int wr, int wc, int fr, int fq) const {
;     ...
;             for (int m = 0; m < 4; ++m) { const int r = row0 + ai * HALF + m * 16;
; #pragma unroll
;                 for (int bj = 0; bj < 2; ++bj) { const int c = col0 + bj * HALF;
;                     const u32x4 gb = *(const u32x4*)(Gb + (size_t)r * ldg + c);
;                     float eb[8];
; #pragma unroll
;                     for (int e = 0; e < 4; ++e) { eb[2 * e] = __builtin_amdgcn_exp2f(-1.4426950408889634f * bf_lo(gb[e])); eb[2 * e + 1] = __builtin_amdgcn_exp2f(-1.4426950408889634f * bf_hi(gb[e])); }
;                     if (u.half == 0) { const u32x4 ga = *(const u32x4*)(Ga + (size_t)r * ldg + c);
; #pragma unroll
;                         for (int e = 0; e < 4; ++e) { const float ea0 = __builtin_amdgcn_exp2f(-1.4426950408889634f * bf_lo(ga[e])), ea1 = __builtin_amdgcn_exp2f(-1.4426950408889634f * bf_hi(ga[e]));
;                             acc[ai][bj][m][e >> 1][(2 * e) & 3] *= (1.0f + eb[2 * e]) * __builtin_amdgcn_rcpf(1.0f + ea0);
;                             acc[ai][bj][m][e >> 1][(2 * e + 1) & 3] *= (1.0f + eb[2 * e + 1]) * __builtin_amdgcn_rcpf(1.0f + ea1); } }
;                     else { u32x4 w;
; #pragma unroll
;                         for (int e = 0; e < 4; ++e) { const float a0 = acc[ai][bj][m][e >> 1][(2 * e) & 3] * __builtin_amdgcn_rcpf(1.0f + eb[2 * e]), a1 = acc[ai][bj][m][e >> 1][(2 * e + 1) & 3] * __builtin_amdgcn_rcpf(1.0f + eb[2 * e + 1]);
;                             w[e] = cvt_pk_bf16(a0, a1); }
;                         *(u32x4*)(O + (size_t)r * ldo + c) = w; } } }
.LBB0_358:
	v_add_u32_e32 v134, 0xa0, v132
	v_mad_i64_i32 v[138:139], s[26:27], v134, s90, 0
	v_lshl_add_u64 v[136:137], v[138:139], 1, s[72:73]
	v_lshl_add_u64 v[136:137], v[2:3], 1, v[136:137]
	v_ashrrev_i32_e32 v135, 31, v134
	v_lshlrev_b64 v[134:135], 11, v[134:135]
	s_and_b64 vcc, exec, s[8:9]
	v_lshl_add_u64 v[134:135], s[74:75], 0, v[134:135]
	s_waitcnt vmcnt(7)
	v_mov_b64_e32 v[140:141], v[174:175]
	v_mov_b64_e32 v[142:143], v[176:177]
	v_lshlrev_b32_e32 v0, 16, v140
	v_and_b32_e32 v133, 0xffff0000, v140
	v_lshlrev_b32_e32 v140, 16, v141
	v_and_b32_e32 v141, 0xffff0000, v141
	v_lshlrev_b32_e32 v144, 16, v142
	v_and_b32_e32 v142, 0xffff0000, v142
	v_lshlrev_b32_e32 v145, 16, v143
	v_and_b32_e32 v143, 0xffff0000, v143
	v_mul_f32_e32 v0, 0xbfb8aa3b, v0
	v_mul_f32_e32 v133, 0xbfb8aa3b, v133
	v_mul_f32_e32 v140, 0xbfb8aa3b, v140
	v_mul_f32_e32 v141, 0xbfb8aa3b, v141
	v_mul_f32_e32 v156, 0xbfb8aa3b, v144
	v_mul_f32_e32 v142, 0xbfb8aa3b, v142
	v_mul_f32_e32 v157, 0xbfb8aa3b, v145
	v_mul_f32_e32 v143, 0xbfb8aa3b, v143
	v_exp_f32_e32 v144, v0
	v_exp_f32_e32 v145, v133
	v_exp_f32_e32 v146, v140
	v_exp_f32_e32 v147, v141
	v_exp_f32_e32 v140, v156
	v_exp_f32_e32 v141, v142
	v_exp_f32_e32 v142, v157
	v_exp_f32_e32 v143, v143
	s_cbranch_vccnz .LBB0_385
	v_add_f32_e32 v0, 1.0, v144
	v_rcp_f32_e32 v156, v0
	v_add_f32_e32 v0, 1.0, v145
	v_rcp_f32_e32 v157, v0
	v_add_f32_e32 v0, 1.0, v146
	v_rcp_f32_e32 v158, v0
	v_add_f32_e32 v0, 1.0, v147
	v_rcp_f32_e32 v159, v0
	v_pk_mul_f32 v[156:157], v[48:49], v[156:157]
	v_add_f32_e32 v0, 1.0, v140
	v_cvt_pk_bf16_f32 v156, v156, v157
	v_pk_mul_f32 v[158:159], v[50:51], v[158:159]
	s_nop 0
	v_cvt_pk_bf16_f32 v157, v158, v159
	v_rcp_f32_e32 v158, v0
	v_add_f32_e32 v0, 1.0, v141
	v_rcp_f32_e32 v159, v0
	v_add_f32_e32 v0, 1.0, v142
	v_rcp_f32_e32 v160, v0
	v_add_f32_e32 v0, 1.0, v143
	v_rcp_f32_e32 v161, v0
	v_pk_mul_f32 v[158:159], v[44:45], v[158:159]
	v_pk_mul_f32 v[160:161], v[46:47], v[160:161]
	v_cvt_pk_bf16_f32 v158, v158, v159
	v_cvt_pk_bf16_f32 v159, v160, v161
	v_lshl_add_u64 v[160:161], v[2:3], 1, v[134:135]
	global_store_dwordx4 v[160:161], v[156:159], off
	v_lshl_add_u64 v[138:139], v[138:139], 1, s[70:71]
	s_cbranch_execnz .LBB0_361
.LBB0_360:
	v_lshl_add_u64 v[156:157], v[2:3], 1, v[138:139]
	v_pk_add_f32 v[144:145], v[144:145], 1.0 op_sel_hi:[1,0]
	v_pk_add_f32 v[146:147], v[146:147], 1.0 op_sel_hi:[1,0]
	v_pk_add_f32 v[142:143], v[142:143], 1.0 op_sel_hi:[1,0]
	v_pk_add_f32 v[140:141], v[140:141], 1.0 op_sel_hi:[1,0]
	s_waitcnt vmcnt(2)
	v_mov_b64_e32 v[156:157], v[222:223]
	v_mov_b64_e32 v[158:159], v[224:225]
	v_lshlrev_b32_e32 v0, 16, v156
	v_mul_f32_e32 v0, 0xbfb8aa3b, v0
	v_and_b32_e32 v133, 0xffff0000, v156
	v_exp_f32_e32 v0, v0
	v_mul_f32_e32 v133, 0xbfb8aa3b, v133
	v_exp_f32_e32 v133, v133
	v_add_f32_e32 v0, 1.0, v0
	v_rcp_f32_e32 v160, v0
	v_add_f32_e32 v0, 1.0, v133
	v_rcp_f32_e32 v161, v0
	v_lshlrev_b32_e32 v0, 16, v157
	v_mul_f32_e32 v0, 0xbfb8aa3b, v0
	v_and_b32_e32 v133, 0xffff0000, v157
	v_exp_f32_e32 v0, v0
	v_mul_f32_e32 v133, 0xbfb8aa3b, v133
	v_exp_f32_e32 v133, v133
	v_pk_mul_f32 v[144:145], v[144:145], v[160:161]
	v_add_f32_e32 v0, 1.0, v0
	v_rcp_f32_e32 v156, v0
	v_add_f32_e32 v0, 1.0, v133
	v_rcp_f32_e32 v157, v0
	v_lshlrev_b32_e32 v0, 16, v158
	v_mul_f32_e32 v0, 0xbfb8aa3b, v0
	v_and_b32_e32 v133, 0xffff0000, v158
	v_exp_f32_e32 v0, v0
	v_mul_f32_e32 v133, 0xbfb8aa3b, v133
	v_exp_f32_e32 v133, v133
	v_pk_mul_f32 v[48:49], v[48:49], v[144:145]
	v_add_f32_e32 v0, 1.0, v0
	v_rcp_f32_e32 v144, v0
	v_add_f32_e32 v0, 1.0, v133
	v_rcp_f32_e32 v145, v0
	v_lshlrev_b32_e32 v0, 16, v159
	v_mul_f32_e32 v0, 0xbfb8aa3b, v0
	v_and_b32_e32 v133, 0xffff0000, v159
	v_exp_f32_e32 v0, v0
	v_mul_f32_e32 v133, 0xbfb8aa3b, v133
	v_exp_f32_e32 v133, v133
	v_pk_mul_f32 v[146:147], v[146:147], v[156:157]
	v_add_f32_e32 v0, 1.0, v0
	v_pk_mul_f32 v[50:51], v[50:51], v[146:147]
	v_rcp_f32_e32 v146, v0
	v_add_f32_e32 v0, 1.0, v133
	v_rcp_f32_e32 v147, v0
	v_pk_mul_f32 v[140:141], v[140:141], v[144:145]
	v_pk_mul_f32 v[142:143], v[142:143], v[146:147]
	s_nop 0
	v_pk_mul_f32 v[46:47], v[46:47], v[142:143]
	v_pk_mul_f32 v[44:45], v[44:45], v[140:141]
.LBB0_361:
	s_and_b64 vcc, exec, s[8:9]
	s_waitcnt vmcnt(7)
	v_mov_b64_e32 v[140:141], v[178:179]
	v_mov_b64_e32 v[142:143], v[180:181]
	v_lshlrev_b32_e32 v0, 16, v140
	v_and_b32_e32 v133, 0xffff0000, v140
	v_lshlrev_b32_e32 v136, 16, v141
	v_and_b32_e32 v137, 0xffff0000, v141
	v_lshlrev_b32_e32 v140, 16, v142
	v_and_b32_e32 v141, 0xffff0000, v142
	v_lshlrev_b32_e32 v142, 16, v143
	v_and_b32_e32 v143, 0xffff0000, v143
	v_mul_f32_e32 v0, 0xbfb8aa3b, v0
	v_mul_f32_e32 v133, 0xbfb8aa3b, v133
	v_mul_f32_e32 v136, 0xbfb8aa3b, v136
	v_mul_f32_e32 v137, 0xbfb8aa3b, v137
	v_mul_f32_e32 v140, 0xbfb8aa3b, v140
	v_mul_f32_e32 v141, 0xbfb8aa3b, v141
	v_mul_f32_e32 v146, 0xbfb8aa3b, v142
	v_mul_f32_e32 v147, 0xbfb8aa3b, v143
	v_exp_f32_e32 v142, v0
	v_exp_f32_e32 v143, v133
	v_exp_f32_e32 v144, v136
	v_exp_f32_e32 v145, v137
	v_exp_f32_e32 v136, v140
	v_exp_f32_e32 v137, v141
	v_exp_f32_e32 v140, v146
	v_exp_f32_e32 v141, v147
	s_cbranch_vccnz .LBB0_386
	v_add_f32_e32 v0, 1.0, v142
	v_rcp_f32_e32 v146, v0
	v_add_f32_e32 v0, 1.0, v143
	v_rcp_f32_e32 v147, v0
	v_add_f32_e32 v0, 1.0, v144
	v_lshl_add_u64 v[134:135], v[2:3], 1, v[134:135]
	v_pk_mul_f32 v[146:147], v[16:17], v[146:147]
	s_nop 0
	v_cvt_pk_bf16_f32 v156, v146, v147
	v_rcp_f32_e32 v146, v0
	v_add_f32_e32 v0, 1.0, v145
	v_rcp_f32_e32 v147, v0
	v_add_f32_e32 v0, 1.0, v136
	v_pk_mul_f32 v[146:147], v[18:19], v[146:147]
	s_nop 0
	v_cvt_pk_bf16_f32 v157, v146, v147
	v_rcp_f32_e32 v146, v0
	v_add_f32_e32 v0, 1.0, v137
	v_rcp_f32_e32 v147, v0
	v_add_f32_e32 v0, 1.0, v140
	v_pk_mul_f32 v[146:147], v[12:13], v[146:147]
	s_nop 0
	v_cvt_pk_bf16_f32 v158, v146, v147
	v_rcp_f32_e32 v146, v0
	v_add_f32_e32 v0, 1.0, v141
	v_rcp_f32_e32 v147, v0
	s_nop 0
	v_pk_mul_f32 v[146:147], v[14:15], v[146:147]
	s_nop 0
	v_cvt_pk_bf16_f32 v159, v146, v147
	global_store_dwordx4 v[134:135], v[156:159], off offset:256
	s_cbranch_execnz .LBB0_364
; __device__ __forceinline__ unsigned cvt_pk_bf16(float lo, float hi) { f32x2 v = {lo, hi}; bf16x2_t b = __builtin_convertvector(v, bf16x2_t); return __builtin_bit_cast(unsigned, b); }
; __device__ __forceinline__ float bf_lo(unsigned w) { return __uint_as_float(w << 16); }
; __device__ __forceinline__ float bf_hi(unsigned w) { return __uint_as_float(w & 0xffff0000u); }
;     __device__ __forceinline__ void operator()(f32x4 (&acc)[2][2][4][2], const Unit& u, int wr, int wc, int fr, int fq) const {
;     ...
;             for (int m = 0; m < 4; ++m) { const int r = row0 + ai * HALF + m * 16;
; #pragma unroll
;                 for (int bj = 0; bj < 2; ++bj) { const int c = col0 + bj * HALF;
;                     const u32x4 gb = *(const u32x4*)(Gb + (size_t)r * ldg + c);
;                     float eb[8];
; #pragma unroll
;                     for (int e = 0; e < 4; ++e) { eb[2 * e] = __builtin_amdgcn_exp2f(-1.4426950408889634f * bf_lo(gb[e])); eb[2 * e + 1] = __builtin_amdgcn_exp2f(-1.4426950408889634f * bf_hi(gb[e])); }
;                     if (u.half == 0) { const u32x4 ga = *(const u32x4*)(Ga + (size_t)r * ldg + c);
; #pragma unroll
;                         for (int e = 0; e < 4; ++e) { const float ea0 = __builtin_amdgcn_exp2f(-1.4426950408889634f * bf_lo(ga[e])), ea1 = __builtin_amdgcn_exp2f(-1.4426950408889634f * bf_hi(ga[e]));
;                             acc[ai][bj][m][e >> 1][(2 * e) & 3] *= (1.0f + eb[2 * e]) * __builtin_amdgcn_rcpf(1.0f + ea0);
;                             acc[ai][bj][m][e >> 1][(2 * e + 1) & 3] *= (1.0f + eb[2 * e + 1]) * __builtin_amdgcn_rcpf(1.0f + ea1); } }
;                     else { u32x4 w;
; #pragma unroll
;                         for (int e = 0; e < 4; ++e) { const float a0 = acc[ai][bj][m][e >> 1][(2 * e) & 3] * __builtin_amdgcn_rcpf(1.0f + eb[2 * e]), a1 = acc[ai][bj][m][e >> 1][(2 * e + 1) & 3] * __builtin_amdgcn_rcpf(1.0f + eb[2 * e + 1]);
;                             w[e] = cvt_pk_bf16(a0, a1); }
;                         *(u32x4*)(O + (size_t)r * ldo + c) = w; } } }
.LBB0_363:
	v_lshl_add_u64 v[134:135], v[2:3], 1, v[138:139]
	v_pk_add_f32 v[142:143], v[142:143], 1.0 op_sel_hi:[1,0]
	v_pk_add_f32 v[144:145], v[144:145], 1.0 op_sel_hi:[1,0]
	v_pk_add_f32 v[140:141], v[140:141], 1.0 op_sel_hi:[1,0]
	v_pk_add_f32 v[136:137], v[136:137], 1.0 op_sel_hi:[1,0]
	s_waitcnt vmcnt(1)
	v_mov_b64_e32 v[156:157], v[230:231]
	v_mov_b64_e32 v[158:159], v[232:233]
	v_lshlrev_b32_e32 v0, 16, v156
	v_mul_f32_e32 v0, 0xbfb8aa3b, v0
	v_and_b32_e32 v133, 0xffff0000, v156
	v_exp_f32_e32 v0, v0
	v_mul_f32_e32 v133, 0xbfb8aa3b, v133
	v_exp_f32_e32 v133, v133
	v_add_f32_e32 v0, 1.0, v0
	v_rcp_f32_e32 v134, v0
	v_add_f32_e32 v0, 1.0, v133
	v_rcp_f32_e32 v135, v0
	v_lshlrev_b32_e32 v0, 16, v157
	v_mul_f32_e32 v0, 0xbfb8aa3b, v0
	v_and_b32_e32 v133, 0xffff0000, v157
	v_exp_f32_e32 v0, v0
	v_mul_f32_e32 v133, 0xbfb8aa3b, v133
	v_exp_f32_e32 v133, v133
	v_pk_mul_f32 v[134:135], v[142:143], v[134:135]
	v_add_f32_e32 v0, 1.0, v0
	v_rcp_f32_e32 v138, v0
	v_add_f32_e32 v0, 1.0, v133
	v_rcp_f32_e32 v139, v0
	v_lshlrev_b32_e32 v0, 16, v158
	v_mul_f32_e32 v0, 0xbfb8aa3b, v0
	v_and_b32_e32 v133, 0xffff0000, v158
	v_exp_f32_e32 v0, v0
	v_mul_f32_e32 v133, 0xbfb8aa3b, v133
	v_exp_f32_e32 v133, v133
	v_pk_mul_f32 v[16:17], v[16:17], v[134:135]
	v_add_f32_e32 v0, 1.0, v0
	v_rcp_f32_e32 v134, v0
	v_add_f32_e32 v0, 1.0, v133
	v_rcp_f32_e32 v135, v0
	v_lshlrev_b32_e32 v0, 16, v159
	v_mul_f32_e32 v0, 0xbfb8aa3b, v0
	v_and_b32_e32 v133, 0xffff0000, v159
	v_exp_f32_e32 v0, v0
	v_mul_f32_e32 v133, 0xbfb8aa3b, v133
	v_exp_f32_e32 v133, v133
	v_pk_mul_f32 v[138:139], v[144:145], v[138:139]
	v_add_f32_e32 v0, 1.0, v0
	v_pk_mul_f32 v[18:19], v[18:19], v[138:139]
	v_rcp_f32_e32 v138, v0
	v_add_f32_e32 v0, 1.0, v133
	v_rcp_f32_e32 v139, v0
	v_pk_mul_f32 v[134:135], v[136:137], v[134:135]
	v_pk_mul_f32 v[136:137], v[140:141], v[138:139]
	s_nop 0
	v_pk_mul_f32 v[14:15], v[14:15], v[136:137]
	v_pk_mul_f32 v[12:13], v[12:13], v[134:135]
.LBB0_364:
	v_add_u32_e32 v132, 0xb0, v132
	v_mad_i64_i32 v[136:137], s[26:27], v132, s90, 0
	v_lshl_add_u64 v[134:135], v[136:137], 1, s[72:73]
	v_lshl_add_u64 v[134:135], v[2:3], 1, v[134:135]
	v_ashrrev_i32_e32 v133, 31, v132
	v_lshlrev_b64 v[132:133], 11, v[132:133]
	s_and_b64 vcc, exec, s[8:9]
	v_lshl_add_u64 v[132:133], s[74:75], 0, v[132:133]
	s_waitcnt vmcnt(7)
	v_mov_b64_e32 v[138:139], v[182:183]
	v_mov_b64_e32 v[140:141], v[184:185]
	v_lshlrev_b32_e32 v0, 16, v138
	v_and_b32_e32 v138, 0xffff0000, v138
	v_lshlrev_b32_e32 v142, 16, v139
	v_and_b32_e32 v139, 0xffff0000, v139
	v_lshlrev_b32_e32 v143, 16, v140
	v_and_b32_e32 v140, 0xffff0000, v140
	v_lshlrev_b32_e32 v144, 16, v141
	v_and_b32_e32 v141, 0xffff0000, v141
	v_mul_f32_e32 v0, 0xbfb8aa3b, v0
	v_mul_f32_e32 v138, 0xbfb8aa3b, v138
	v_mul_f32_e32 v145, 0xbfb8aa3b, v142
	v_mul_f32_e32 v139, 0xbfb8aa3b, v139
	v_mul_f32_e32 v146, 0xbfb8aa3b, v143
	v_mul_f32_e32 v140, 0xbfb8aa3b, v140
	v_mul_f32_e32 v147, 0xbfb8aa3b, v144
	v_mul_f32_e32 v141, 0xbfb8aa3b, v141
	v_exp_f32_e32 v142, v0
	v_exp_f32_e32 v143, v138
	v_exp_f32_e32 v144, v145
	v_exp_f32_e32 v145, v139
	v_exp_f32_e32 v138, v146
	v_exp_f32_e32 v139, v140
	v_exp_f32_e32 v140, v147
	v_exp_f32_e32 v141, v141
	s_cbranch_vccnz .LBB0_387
	v_add_f32_e32 v0, 1.0, v142
	v_rcp_f32_e32 v146, v0
	v_add_f32_e32 v0, 1.0, v143
	v_rcp_f32_e32 v147, v0
	v_add_f32_e32 v0, 1.0, v144
	v_pk_mul_f32 v[146:147], v[40:41], v[146:147]
	s_nop 0
	v_cvt_pk_bf16_f32 v156, v146, v147
	v_rcp_f32_e32 v146, v0
	v_add_f32_e32 v0, 1.0, v145
	v_rcp_f32_e32 v147, v0
	v_add_f32_e32 v0, 1.0, v138
	v_pk_mul_f32 v[146:147], v[42:43], v[146:147]
	s_nop 0
	v_cvt_pk_bf16_f32 v157, v146, v147
	v_rcp_f32_e32 v146, v0
	v_add_f32_e32 v0, 1.0, v139
	v_rcp_f32_e32 v147, v0
	v_add_f32_e32 v0, 1.0, v140
	v_pk_mul_f32 v[146:147], v[36:37], v[146:147]
	s_nop 0
	v_cvt_pk_bf16_f32 v158, v146, v147
	v_rcp_f32_e32 v146, v0
	v_add_f32_e32 v0, 1.0, v141
	v_rcp_f32_e32 v147, v0
	s_nop 0
	v_pk_mul_f32 v[146:147], v[38:39], v[146:147]
	s_nop 0
	v_cvt_pk_bf16_f32 v159, v146, v147
	v_lshl_add_u64 v[146:147], v[2:3], 1, v[132:133]
	global_store_dwordx4 v[146:147], v[156:159], off
	v_lshl_add_u64 v[136:137], v[136:137], 1, s[70:71]
	s_cbranch_execnz .LBB0_367
; __device__ __forceinline__ unsigned cvt_pk_bf16(float lo, float hi) { f32x2 v = {lo, hi}; bf16x2_t b = __builtin_convertvector(v, bf16x2_t); return __builtin_bit_cast(unsigned, b); }
; __device__ __forceinline__ float bf_lo(unsigned w) { return __uint_as_float(w << 16); }
; __device__ __forceinline__ float bf_hi(unsigned w) { return __uint_as_float(w & 0xffff0000u); }
;     __device__ __forceinline__ void operator()(f32x4 (&acc)[2][2][4][2], const Unit& u, int wr, int wc, int fr, int fq) const {
;     ...
;             for (int m = 0; m < 4; ++m) { const int r = row0 + ai * HALF + m * 16;
; #pragma unroll
;                 for (int bj = 0; bj < 2; ++bj) { const int c = col0 + bj * HALF;
;                     const u32x4 gb = *(const u32x4*)(Gb + (size_t)r * ldg + c);
;                     float eb[8];
; #pragma unroll
;                     for (int e = 0; e < 4; ++e) { eb[2 * e] = __builtin_amdgcn_exp2f(-1.4426950408889634f * bf_lo(gb[e])); eb[2 * e + 1] = __builtin_amdgcn_exp2f(-1.4426950408889634f * bf_hi(gb[e])); }
;                     if (u.half == 0) { const u32x4 ga = *(const u32x4*)(Ga + (size_t)r * ldg + c);
; #pragma unroll
;                         for (int e = 0; e < 4; ++e) { const float ea0 = __builtin_amdgcn_exp2f(-1.4426950408889634f * bf_lo(ga[e])), ea1 = __builtin_amdgcn_exp2f(-1.4426950408889634f * bf_hi(ga[e]));
;                             acc[ai][bj][m][e >> 1][(2 * e) & 3] *= (1.0f + eb[2 * e]) * __builtin_amdgcn_rcpf(1.0f + ea0);
;                             acc[ai][bj][m][e >> 1][(2 * e + 1) & 3] *= (1.0f + eb[2 * e + 1]) * __builtin_amdgcn_rcpf(1.0f + ea1); } }
;                     else { u32x4 w;
; #pragma unroll
;                         for (int e = 0; e < 4; ++e) { const float a0 = acc[ai][bj][m][e >> 1][(2 * e) & 3] * __builtin_amdgcn_rcpf(1.0f + eb[2 * e]), a1 = acc[ai][bj][m][e >> 1][(2 * e + 1) & 3] * __builtin_amdgcn_rcpf(1.0f + eb[2 * e + 1]);
;                             w[e] = cvt_pk_bf16(a0, a1); }
;                         *(u32x4*)(O + (size_t)r * ldo + c) = w; } } }
.LBB0_366:
	v_lshl_add_u64 v[146:147], v[2:3], 1, v[136:137]
	v_pk_add_f32 v[142:143], v[142:143], 1.0 op_sel_hi:[1,0]
	v_pk_add_f32 v[144:145], v[144:145], 1.0 op_sel_hi:[1,0]
	v_pk_add_f32 v[140:141], v[140:141], 1.0 op_sel_hi:[1,0]
	v_pk_add_f32 v[138:139], v[138:139], 1.0 op_sel_hi:[1,0]
	s_waitcnt vmcnt(0)
	v_mov_b64_e32 v[156:157], v[234:235]
	v_mov_b64_e32 v[158:159], v[236:237]
	v_lshlrev_b32_e32 v0, 16, v156
	v_mul_f32_e32 v0, 0xbfb8aa3b, v0
	v_and_b32_e32 v146, 0xffff0000, v156
	v_exp_f32_e32 v0, v0
	v_mul_f32_e32 v146, 0xbfb8aa3b, v146
	v_exp_f32_e32 v147, v146
	v_and_b32_e32 v156, 0xffff0000, v157
	v_add_f32_e32 v0, 1.0, v0
	v_rcp_f32_e32 v146, v0
	v_add_f32_e32 v0, 1.0, v147
	v_rcp_f32_e32 v147, v0
	v_lshlrev_b32_e32 v0, 16, v157
	v_mul_f32_e32 v0, 0xbfb8aa3b, v0
	v_exp_f32_e32 v0, v0
	v_mul_f32_e32 v156, 0xbfb8aa3b, v156
	v_exp_f32_e32 v157, v156
	v_pk_mul_f32 v[142:143], v[142:143], v[146:147]
	v_add_f32_e32 v0, 1.0, v0
	v_rcp_f32_e32 v156, v0
	v_add_f32_e32 v0, 1.0, v157
	v_rcp_f32_e32 v157, v0
	v_lshlrev_b32_e32 v0, 16, v158
	v_pk_mul_f32 v[40:41], v[40:41], v[142:143]
	v_mul_f32_e32 v0, 0xbfb8aa3b, v0
	v_and_b32_e32 v142, 0xffff0000, v158
	v_exp_f32_e32 v0, v0
	v_mul_f32_e32 v142, 0xbfb8aa3b, v142
	v_exp_f32_e32 v143, v142
	v_pk_mul_f32 v[144:145], v[144:145], v[156:157]
	v_add_f32_e32 v0, 1.0, v0
	v_rcp_f32_e32 v142, v0
	v_add_f32_e32 v0, 1.0, v143
	v_rcp_f32_e32 v143, v0
	v_lshlrev_b32_e32 v0, 16, v159
	v_pk_mul_f32 v[42:43], v[42:43], v[144:145]
	v_mul_f32_e32 v0, 0xbfb8aa3b, v0
	v_and_b32_e32 v144, 0xffff0000, v159
	v_exp_f32_e32 v0, v0
	v_mul_f32_e32 v144, 0xbfb8aa3b, v144
	v_exp_f32_e32 v145, v144
	v_pk_mul_f32 v[138:139], v[138:139], v[142:143]
	v_add_f32_e32 v0, 1.0, v0
	v_rcp_f32_e32 v144, v0
	v_add_f32_e32 v0, 1.0, v145
	v_rcp_f32_e32 v145, v0
	v_pk_mul_f32 v[36:37], v[36:37], v[138:139]
	v_pk_mul_f32 v[140:141], v[140:141], v[144:145]
	s_nop 0
	v_pk_mul_f32 v[38:39], v[38:39], v[140:141]
.LBB0_367:
	s_and_b64 vcc, exec, s[8:9]
	s_waitcnt vmcnt(7)
	v_mov_b64_e32 v[138:139], v[186:187]
	v_mov_b64_e32 v[140:141], v[188:189]
	v_lshlrev_b32_e32 v0, 16, v138
	v_and_b32_e32 v134, 0xffff0000, v138
	v_lshlrev_b32_e32 v135, 16, v139
	v_and_b32_e32 v138, 0xffff0000, v139
	v_lshlrev_b32_e32 v139, 16, v140
	v_and_b32_e32 v140, 0xffff0000, v140
	v_lshlrev_b32_e32 v142, 16, v141
	v_and_b32_e32 v141, 0xffff0000, v141
	v_mul_f32_e32 v0, 0xbfb8aa3b, v0
	v_mul_f32_e32 v134, 0xbfb8aa3b, v134
	v_mul_f32_e32 v135, 0xbfb8aa3b, v135
	v_mul_f32_e32 v138, 0xbfb8aa3b, v138
	v_mul_f32_e32 v139, 0xbfb8aa3b, v139
	v_mul_f32_e32 v144, 0xbfb8aa3b, v140
	v_mul_f32_e32 v145, 0xbfb8aa3b, v142
	v_mul_f32_e32 v146, 0xbfb8aa3b, v141
	v_exp_f32_e32 v140, v0
	v_exp_f32_e32 v141, v134
	v_exp_f32_e32 v142, v135
	v_exp_f32_e32 v143, v138
	v_exp_f32_e32 v134, v139
	v_exp_f32_e32 v135, v144
	v_exp_f32_e32 v138, v145
	v_exp_f32_e32 v139, v146
	s_cbranch_vccnz .LBB0_388
	v_add_f32_e32 v0, 1.0, v140
	v_rcp_f32_e32 v144, v0
	v_add_f32_e32 v0, 1.0, v141
	v_rcp_f32_e32 v145, v0
	v_add_f32_e32 v0, 1.0, v142
	v_rcp_f32_e32 v146, v0
	v_add_f32_e32 v0, 1.0, v143
	v_rcp_f32_e32 v147, v0
	v_pk_mul_f32 v[144:145], v[8:9], v[144:145]
	v_add_f32_e32 v0, 1.0, v134
	v_cvt_pk_bf16_f32 v144, v144, v145
	v_pk_mul_f32 v[146:147], v[10:11], v[146:147]
	v_lshl_add_u64 v[132:133], v[2:3], 1, v[132:133]
	v_cvt_pk_bf16_f32 v145, v146, v147
	v_rcp_f32_e32 v146, v0
	v_add_f32_e32 v0, 1.0, v135
	v_rcp_f32_e32 v147, v0
	v_add_f32_e32 v0, 1.0, v138
	v_rcp_f32_e32 v156, v0
	v_add_f32_e32 v0, 1.0, v139
	v_rcp_f32_e32 v157, v0
	v_pk_mul_f32 v[146:147], v[4:5], v[146:147]
	s_nop 0
	v_cvt_pk_bf16_f32 v146, v146, v147
	v_pk_mul_f32 v[156:157], v[6:7], v[156:157]
	s_nop 0
	v_cvt_pk_bf16_f32 v147, v156, v157
	global_store_dwordx4 v[132:133], v[144:147], off offset:256
	s_cbranch_execnz .LBB0_370

; __global__ void __launch_bounds__(NTHREADS, 2) fwd_megakernel(Params P, int ph_lo, int ph_hi, int use_sync) {
	.amdhsa_kernel _Z14fwd_megakernel6Paramsiii
		.amdhsa_group_segment_fixed_size 0
		.amdhsa_private_segment_fixed_size 0
		.amdhsa_kernarg_size 432
		.amdhsa_user_sgpr_count 2
		.amdhsa_user_sgpr_dispatch_ptr 0
		.amdhsa_user_sgpr_queue_ptr 0
		.amdhsa_user_sgpr_kernarg_segment_ptr 1
		.amdhsa_user_sgpr_dispatch_id 0
		.amdhsa_user_sgpr_kernarg_preload_length 0
		.amdhsa_user_sgpr_kernarg_preload_offset 0
		.amdhsa_user_sgpr_private_segment_size 0
		.amdhsa_uses_dynamic_stack 0
		.amdhsa_enable_private_segment 0
		.amdhsa_system_sgpr_workgroup_id_x 1
		.amdhsa_system_sgpr_workgroup_id_y 0
		.amdhsa_system_sgpr_workgroup_id_z 0
		.amdhsa_system_sgpr_workgroup_info 0
		.amdhsa_system_vgpr_workitem_id 2
		.amdhsa_next_free_vgpr 248
		.amdhsa_next_free_sgpr 100
		.amdhsa_accum_offset 248
		.amdhsa_reserve_vcc 1
		.amdhsa_float_round_mode_32 0
		.amdhsa_float_round_mode_16_64 0
		.amdhsa_float_denorm_mode_32 3
		.amdhsa_float_denorm_mode_16_64 3
		.amdhsa_dx10_clamp 1
		.amdhsa_ieee_mode 1
		.amdhsa_fp16_overflow 0
		.amdhsa_tg_split 0
		.amdhsa_exception_fp_ieee_invalid_op 0
		.amdhsa_exception_fp_denorm_src 0
		.amdhsa_exception_fp_ieee_div_zero 0
		.amdhsa_exception_fp_ieee_overflow 0
		.amdhsa_exception_fp_ieee_underflow 0
		.amdhsa_exception_fp_ieee_inexact 0
		.amdhsa_exception_int_div_zero 0
	.end_amdhsa_kernel

; __global__ void __launch_bounds__(NTHREADS, 2) fwd_megakernel(Params P, int ph_lo, int ph_hi, int use_sync) {
amdhsa.kernels:
  - .agpr_count:     0
    .args:
      - .offset:         0
        .size:           160
        .value_kind:     by_value
      - .offset:         160
        .size:           4
        .value_kind:     by_value
      - .offset:         164
        .size:           4
        .value_kind:     by_value
      - .offset:         168
        .size:           4
        .value_kind:     by_value
      - .offset:         176
        .size:           4
        .value_kind:     hidden_block_count_x
      - .offset:         180
        .size:           4
        .value_kind:     hidden_block_count_y
      - .offset:         184
        .size:           4
        .value_kind:     hidden_block_count_z
      - .offset:         188
        .size:           2
        .value_kind:     hidden_group_size_x
      - .offset:         190
        .size:           2
        .value_kind:     hidden_group_size_y
      - .offset:         192
        .size:           2
        .value_kind:     hidden_group_size_z
      - .offset:         194
        .size:           2
        .value_kind:     hidden_remainder_x
      - .offset:         196
        .size:           2
        .value_kind:     hidden_remainder_y
      - .offset:         198
        .size:           2
        .value_kind:     hidden_remainder_z
      - .offset:         216
        .size:           8
        .value_kind:     hidden_global_offset_x
      - .offset:         224
        .size:           8
        .value_kind:     hidden_global_offset_y
      - .offset:         232
        .size:           8
        .value_kind:     hidden_global_offset_z
      - .offset:         240
        .size:           2
        .value_kind:     hidden_grid_dims
      - .offset:         264
        .size:           8
        .value_kind:     hidden_multigrid_sync_arg
      - .offset:         296
        .size:           4
        .value_kind:     hidden_dynamic_lds_size
    .group_segment_fixed_size: 0
    .kernarg_segment_align: 8
    .kernarg_segment_size: 432
    .language:       OpenCL C
    .language_version:
      - 2
      - 0
    .max_flat_workgroup_size: 512
    .name:           _Z14fwd_megakernel6Paramsiii
    .private_segment_fixed_size: 0
    .sgpr_count:     106
    .sgpr_spill_count: 108
    .symbol:         _Z14fwd_megakernel6Paramsiii.kd
    .uniform_work_group_size: 1
    .uses_dynamic_stack: false
    .vgpr_count:     248
    .vgpr_spill_count: 0
    .wavefront_size: 64
